# cache-policy hints: nt on the touch-once global loads/stores of the norm phases (P1,P8,P11) and of the GEMM epilogues of P7,P9,P10
# baseline (speedup 1.0000x reference)
.LBB0_183:
	global_load_dwordx4 v[30:33], v34, s[8:9] nt
	global_load_dwordx4 v[26:29], v34, s[8:9] offset:1024 nt
	global_load_dwordx4 v[22:25], v34, s[8:9] offset:2048 nt
	global_load_dwordx4 v[18:21], v34, s[8:9] offset:3072 nt
	v_lshl_add_u64 v[2:3], s[8:9], 0, v[34:35]
	v_add_co_u32_e32 v74, vcc, s12, v2
	s_lshl_b64 s[0:1], s[0:1], 2
	s_nop 0
	v_addc_co_u32_e32 v75, vcc, 0, v3, vcc
	global_load_dwordx4 v[14:17], v[74:75], off nt
	global_load_dwordx4 v[10:13], v[74:75], off offset:1024 nt
	global_load_dwordx4 v[2:5], v[74:75], off offset:3072 nt
	global_load_dwordx4 v[6:9], v[74:75], off offset:2048 nt
	s_add_u32 s8, s30, s0
	s_addc_u32 s9, s31, s1
	s_ashr_i32 s7, s6, 31
	s_lshl_b64 s[0:1], s[6:7], 12
	s_add_u32 s10, s8, 0x2000
	global_load_dwordx4 v[92:95], v[38:39], off nt
	global_load_dwordx4 v[96:99], v[40:41], off nt
	global_load_dwordx4 v[100:103], v[42:43], off nt
	s_addc_u32 s11, s9, 0
	global_load_dwordx4 v[104:107], v84, s[8:9] nt
	global_load_dwordx4 v[108:111], v84, s[10:11] nt
	s_add_i32 s6, s6, s68
	s_cmpk_lt_i32 s6, 0x4200
	s_waitcnt vmcnt(12)
	v_mov_b32_e32 v112, v31
	s_waitcnt vmcnt(11)
	v_mov_b32_e32 v113, v27
	v_mov_b32_e32 v116, v33
	v_mov_b32_e32 v117, v29
	v_mov_b32_e32 v74, v30
	v_mov_b32_e32 v75, v26
	v_mov_b32_e32 v114, v32
	v_mov_b32_e32 v115, v28
	s_waitcnt vmcnt(10)
	v_pk_mul_f32 v[118:119], v[24:25], v[24:25]
	v_pk_mul_f32 v[120:121], v[22:23], v[22:23]
	v_pk_mul_f32 v[112:113], v[112:113], v[112:113]
	v_pk_mul_f32 v[116:117], v[116:117], v[116:117]
	v_pk_mov_b32 v[124:125], v[120:121], v[118:119] op_sel:[1,0]
	v_mov_b32_e32 v121, v119
	v_pk_fma_f32 v[74:75], v[74:75], v[74:75], v[112:113]
	v_pk_fma_f32 v[112:113], v[114:115], v[114:115], v[116:117]
	s_waitcnt vmcnt(9)
	v_mul_f32_e32 v76, v19, v19
	v_mul_f32_e32 v122, v21, v21
	v_pk_add_f32 v[114:115], v[124:125], v[120:121]
	v_pk_add_f32 v[74:75], v[74:75], v[112:113]
	v_pk_fma_f32 v[118:119], v[18:19], v[18:19], v[76:77] op_sel_hi:[1,1,0]
	v_pk_fma_f32 v[122:123], v[20:21], v[20:21], v[122:123] op_sel_hi:[1,1,0]
	s_waitcnt vmcnt(8)
	v_mul_f32_e32 v126, v14, v14
	v_mul_f32_e32 v127, v15, v15
	v_pk_add_f32 v[112:113], v[114:115], v[114:115] op_sel:[0,1] op_sel_hi:[1,0]
	v_pk_add_f32 v[74:75], v[74:75], v[74:75] op_sel:[0,1] op_sel_hi:[1,0]
	v_mul_f32_e32 v119, v16, v16
	v_mul_f32_e32 v123, v17, v17
	s_waitcnt vmcnt(7)
	v_pk_mul_f32 v[116:117], v[12:13], v[12:13]
	v_pk_mul_f32 v[120:121], v[10:11], v[10:11]
	v_mov_b32_e32 v113, v127
	v_mov_b32_e32 v75, v126
	v_pk_mov_b32 v[114:115], v[120:121], v[116:117] op_sel:[1,0]
	v_mov_b32_e32 v121, v117
	v_pk_add_f32 v[118:119], v[118:119], v[122:123]
	v_pk_add_f32 v[74:75], v[74:75], v[112:113]
	s_waitcnt vmcnt(5)
	v_mul_f32_e32 v76, v7, v7
	v_mul_f32_e32 v124, v9, v9
	v_pk_add_f32 v[114:115], v[114:115], v[120:121]
	v_pk_add_f32 v[74:75], v[74:75], v[118:119]
	v_mul_f32_e32 v128, v2, v2
	v_mul_f32_e32 v129, v3, v3
	v_mul_f32_e32 v130, v4, v4
	v_mul_f32_e32 v131, v5, v5
	v_pk_fma_f32 v[116:117], v[6:7], v[6:7], v[76:77] op_sel_hi:[1,1,0]
	v_pk_fma_f32 v[124:125], v[8:9], v[8:9], v[124:125] op_sel_hi:[1,1,0]
	v_pk_add_f32 v[114:115], v[114:115], v[114:115] op_sel:[0,1] op_sel_hi:[1,0]
	v_pk_add_f32 v[74:75], v[74:75], v[74:75] op_sel:[0,1] op_sel_hi:[1,0]
	v_mov_b32_e32 v117, v130
	v_mov_b32_e32 v125, v131
	v_mov_b32_e32 v115, v129
	v_mov_b32_e32 v75, v128
	v_pk_add_f32 v[116:117], v[116:117], v[124:125]
	v_pk_add_f32 v[74:75], v[74:75], v[114:115]
	s_waitcnt vmcnt(1)
	v_pk_add_f32 v[96:97], v[104:105], v[96:97]
	v_pk_add_f32 v[74:75], v[74:75], v[116:117]
	v_pk_add_f32 v[98:99], v[106:107], v[98:99]
	v_add_f32_e32 v74, v74, v75
	ds_bpermute_b32 v75, v1, v74
	s_waitcnt vmcnt(0)
	v_pk_add_f32 v[100:101], v[108:109], v[100:101]
	v_pk_add_f32 v[102:103], v[110:111], v[102:103]
	v_pk_add_f32 v[100:101], v[100:101], 1.0 op_sel_hi:[1,0]
	v_pk_add_f32 v[102:103], v[102:103], 1.0 op_sel_hi:[1,0]
	s_waitcnt lgkmcnt(0)
	v_add_f32_e32 v74, v74, v75
	ds_bpermute_b32 v75, v77, v74
	s_waitcnt lgkmcnt(0)
	v_add_f32_e32 v74, v74, v75
	ds_bpermute_b32 v75, v78, v74
	s_waitcnt lgkmcnt(0)
	v_add_f32_e32 v74, v74, v75
	ds_bpermute_b32 v75, v79, v74
	s_waitcnt lgkmcnt(0)
	v_add_f32_e32 v74, v74, v75
	ds_bpermute_b32 v75, v80, v74
	s_waitcnt lgkmcnt(0)
	v_add_f32_e32 v76, v74, v75
	ds_bpermute_b32 v112, v81, v76
	v_lshl_add_u64 v[74:75], v[36:37], 0, s[0:1]
	s_waitcnt lgkmcnt(0)
	v_add_f32_e32 v76, v76, v112
	v_fmamk_f32 v76, v76, 0x3a000000, v82
	v_mul_f32_e32 v104, 0x4f800000, v76
	v_cmp_gt_f32_e32 vcc, s13, v76
	s_nop 1
	v_cndmask_b32_e32 v76, v76, v104, vcc
	v_sqrt_f32_e32 v104, v76
	s_nop 0
	v_add_u32_e32 v105, -1, v104
	v_add_u32_e32 v106, 1, v104
	v_fma_f32 v107, -v105, v104, v76
	v_fma_f32 v108, -v106, v104, v76
	v_cmp_ge_f32_e64 s[0:1], 0, v107
	s_nop 1
	v_cndmask_b32_e64 v104, v104, v105, s[0:1]
	v_cmp_lt_f32_e64 s[0:1], 0, v108
	s_nop 1
	v_cndmask_b32_e64 v104, v104, v106, s[0:1]
	v_mul_f32_e32 v105, 0x37800000, v104
	v_cndmask_b32_e32 v104, v104, v105, vcc
	v_cmp_class_f32_e32 vcc, v76, v83
	s_nop 1
	v_cndmask_b32_e32 v76, v104, v76, vcc
	v_div_scale_f32 v104, s[0:1], v76, v76, 1.0
	v_rcp_f32_e32 v105, v104
	v_div_scale_f32 v106, vcc, 1.0, v76, 1.0
	v_fma_f32 v107, -v104, v105, 1.0
	v_fmac_f32_e32 v105, v107, v105
	v_mul_f32_e32 v107, v106, v105
	v_fma_f32 v108, -v104, v107, v106
	v_fmac_f32_e32 v107, v108, v105
	v_fma_f32 v104, -v104, v107, v106
	v_div_fmas_f32 v104, v104, v105, v107
	v_div_fixup_f32 v76, v104, v76, 1.0
	v_pk_mul_f32 v[30:31], v[30:31], v[76:77] op_sel_hi:[1,0]
	v_pk_mul_f32 v[32:33], v[32:33], v[76:77] op_sel_hi:[1,0]
	v_pk_mul_f32 v[30:31], v[92:93], v[30:31]
	v_pk_mul_f32 v[32:33], v[94:95], v[32:33]
	v_pk_fma_f32 v[30:31], v[100:101], v[30:31], v[96:97]
	v_pk_fma_f32 v[32:33], v[102:103], v[32:33], v[98:99]
	v_cvt_pk_bf16_f32 v30, v30, v31
	v_pk_mul_f32 v[26:27], v[26:27], v[76:77] op_sel_hi:[1,0]
	v_cvt_pk_bf16_f32 v31, v32, v33
	global_store_dwordx2 v[74:75], v[30:31], off nt
	global_load_dwordx4 v[30:33], v[38:39], off offset:1024 nt
	s_nop 0
	global_load_dwordx4 v[92:95], v[40:41], off offset:1024 nt
	global_load_dwordx4 v[96:99], v84, s[8:9] offset:1024 nt
	global_load_dwordx4 v[100:103], v85, s[10:11] nt
	global_load_dwordx4 v[104:107], v[44:45], off nt
	v_pk_mul_f32 v[28:29], v[28:29], v[76:77] op_sel_hi:[1,0]
	v_pk_mul_f32 v[22:23], v[22:23], v[76:77] op_sel_hi:[1,0]
	v_pk_mul_f32 v[24:25], v[24:25], v[76:77] op_sel_hi:[1,0]
	v_pk_mul_f32 v[18:19], v[18:19], v[76:77] op_sel_hi:[1,0]
	v_pk_mul_f32 v[20:21], v[20:21], v[76:77] op_sel_hi:[1,0]
	v_pk_mul_f32 v[14:15], v[14:15], v[76:77] op_sel_hi:[1,0]
	v_pk_mul_f32 v[16:17], v[16:17], v[76:77] op_sel_hi:[1,0]
	v_pk_mul_f32 v[10:11], v[10:11], v[76:77] op_sel_hi:[1,0]
	v_pk_mul_f32 v[12:13], v[12:13], v[76:77] op_sel_hi:[1,0]
	v_pk_mul_f32 v[6:7], v[6:7], v[76:77] op_sel_hi:[1,0]
	v_pk_mul_f32 v[8:9], v[8:9], v[76:77] op_sel_hi:[1,0]
	v_pk_mul_f32 v[2:3], v[2:3], v[76:77] op_sel_hi:[1,0]
	v_pk_mul_f32 v[4:5], v[4:5], v[76:77] op_sel_hi:[1,0]
	s_waitcnt vmcnt(4)
	v_pk_mul_f32 v[26:27], v[30:31], v[26:27]
	v_pk_mul_f32 v[28:29], v[32:33], v[28:29]
	s_waitcnt vmcnt(2)
	v_pk_add_f32 v[30:31], v[98:99], v[94:95]
	v_pk_add_f32 v[32:33], v[96:97], v[92:93]
	s_waitcnt vmcnt(0)
	v_pk_add_f32 v[94:95], v[100:101], v[104:105]
	v_pk_add_f32 v[92:93], v[102:103], v[106:107]
	v_pk_add_f32 v[94:95], v[94:95], 1.0 op_sel_hi:[1,0]
	v_pk_add_f32 v[92:93], v[92:93], 1.0 op_sel_hi:[1,0]
	v_pk_fma_f32 v[26:27], v[26:27], v[94:95], v[32:33]
	v_pk_fma_f32 v[28:29], v[28:29], v[92:93], v[30:31]
	v_cvt_pk_bf16_f32 v26, v26, v27
	s_nop 0
	v_cvt_pk_bf16_f32 v27, v28, v29
	global_store_dwordx2 v[74:75], v[26:27], off offset:512 nt
	global_load_dwordx4 v[26:29], v[38:39], off offset:2048 nt
	s_nop 0
	global_load_dwordx4 v[30:33], v[40:41], off offset:2048 nt
	global_load_dwordx4 v[92:95], v84, s[8:9] offset:2048 nt
	global_load_dwordx4 v[96:99], v86, s[10:11] nt
	global_load_dwordx4 v[100:103], v[46:47], off nt
	s_waitcnt vmcnt(4)
	v_pk_mul_f32 v[22:23], v[22:23], v[26:27]
	v_pk_mul_f32 v[24:25], v[24:25], v[28:29]
	s_waitcnt vmcnt(2)
	v_pk_add_f32 v[26:27], v[94:95], v[32:33]
	v_pk_add_f32 v[28:29], v[92:93], v[30:31]
	s_waitcnt vmcnt(0)
	v_pk_add_f32 v[32:33], v[96:97], v[100:101]
	v_pk_add_f32 v[30:31], v[98:99], v[102:103]
	v_pk_add_f32 v[32:33], v[32:33], 1.0 op_sel_hi:[1,0]
	v_pk_add_f32 v[30:31], v[30:31], 1.0 op_sel_hi:[1,0]
	v_pk_fma_f32 v[22:23], v[22:23], v[32:33], v[28:29]
	v_pk_fma_f32 v[24:25], v[24:25], v[30:31], v[26:27]
	v_cvt_pk_bf16_f32 v22, v22, v23
	s_nop 0
	v_cvt_pk_bf16_f32 v23, v24, v25
	global_store_dwordx2 v[74:75], v[22:23], off offset:1024 nt
	global_load_dwordx4 v[22:25], v[38:39], off offset:3072 nt
	s_nop 0
	global_load_dwordx4 v[26:29], v[40:41], off offset:3072 nt
	global_load_dwordx4 v[30:33], v84, s[8:9] offset:3072 nt
	global_load_dwordx4 v[92:95], v87, s[10:11] nt
	global_load_dwordx4 v[96:99], v[48:49], off nt
	s_waitcnt vmcnt(4)
	v_pk_mul_f32 v[18:19], v[18:19], v[22:23]
	v_pk_mul_f32 v[20:21], v[20:21], v[24:25]
	s_waitcnt vmcnt(2)
	v_pk_add_f32 v[22:23], v[32:33], v[28:29]
	v_pk_add_f32 v[24:25], v[30:31], v[26:27]
	s_waitcnt vmcnt(0)
	v_pk_add_f32 v[28:29], v[92:93], v[96:97]
	v_pk_add_f32 v[26:27], v[94:95], v[98:99]
	v_pk_add_f32 v[28:29], v[28:29], 1.0 op_sel_hi:[1,0]
	v_pk_add_f32 v[26:27], v[26:27], 1.0 op_sel_hi:[1,0]
	v_pk_fma_f32 v[18:19], v[18:19], v[28:29], v[24:25]
	v_pk_fma_f32 v[20:21], v[20:21], v[26:27], v[22:23]
	v_cvt_pk_bf16_f32 v18, v18, v19
	s_nop 0
	v_cvt_pk_bf16_f32 v19, v20, v21
	global_store_dwordx2 v[74:75], v[18:19], off offset:1536 nt
	global_load_dwordx4 v[18:21], v[50:51], off nt
	s_nop 0
	global_load_dwordx4 v[22:25], v[52:53], off nt
	global_load_dwordx4 v[26:29], v88, s[8:9] nt
	global_load_dwordx4 v[30:33], v88, s[10:11] nt
	global_load_dwordx4 v[92:95], v[54:55], off nt
	s_waitcnt vmcnt(4)
	v_pk_mul_f32 v[14:15], v[14:15], v[18:19]
	v_pk_mul_f32 v[16:17], v[16:17], v[20:21]
	s_waitcnt vmcnt(2)
	v_pk_add_f32 v[18:19], v[28:29], v[24:25]
	v_pk_add_f32 v[20:21], v[26:27], v[22:23]
	s_waitcnt vmcnt(0)
	v_pk_add_f32 v[24:25], v[30:31], v[92:93]
	v_pk_add_f32 v[22:23], v[32:33], v[94:95]
	v_pk_add_f32 v[24:25], v[24:25], 1.0 op_sel_hi:[1,0]
	v_pk_add_f32 v[22:23], v[22:23], 1.0 op_sel_hi:[1,0]
	v_pk_fma_f32 v[14:15], v[14:15], v[24:25], v[20:21]
	v_pk_fma_f32 v[16:17], v[16:17], v[22:23], v[18:19]
	v_cvt_pk_bf16_f32 v14, v14, v15
	s_nop 0
	v_cvt_pk_bf16_f32 v15, v16, v17
	global_store_dwordx2 v[74:75], v[14:15], off offset:2048 nt
	global_load_dwordx4 v[14:17], v[56:57], off nt
	s_nop 0
	global_load_dwordx4 v[18:21], v[58:59], off nt
	global_load_dwordx4 v[22:25], v89, s[8:9] nt
	global_load_dwordx4 v[26:29], v89, s[10:11] nt
	global_load_dwordx4 v[30:33], v[60:61], off nt
	s_waitcnt vmcnt(4)
	v_pk_mul_f32 v[10:11], v[10:11], v[14:15]
	v_pk_mul_f32 v[12:13], v[12:13], v[16:17]
	s_waitcnt vmcnt(2)
	v_pk_add_f32 v[14:15], v[24:25], v[20:21]
	v_pk_add_f32 v[16:17], v[22:23], v[18:19]
	s_waitcnt vmcnt(0)
	v_pk_add_f32 v[20:21], v[26:27], v[30:31]
	v_pk_add_f32 v[18:19], v[28:29], v[32:33]
	v_pk_add_f32 v[20:21], v[20:21], 1.0 op_sel_hi:[1,0]
	v_pk_add_f32 v[18:19], v[18:19], 1.0 op_sel_hi:[1,0]
	v_pk_fma_f32 v[10:11], v[10:11], v[20:21], v[16:17]
	v_pk_fma_f32 v[12:13], v[12:13], v[18:19], v[14:15]
	v_cvt_pk_bf16_f32 v10, v10, v11
	s_nop 0
	v_cvt_pk_bf16_f32 v11, v12, v13
	global_store_dwordx2 v[74:75], v[10:11], off offset:2560 nt
	global_load_dwordx4 v[10:13], v[62:63], off nt
	s_nop 0
	global_load_dwordx4 v[14:17], v[64:65], off nt
	global_load_dwordx4 v[18:21], v90, s[8:9] nt
	global_load_dwordx4 v[22:25], v90, s[10:11] nt
	global_load_dwordx4 v[26:29], v[66:67], off nt
	s_waitcnt vmcnt(4)
	v_pk_mul_f32 v[6:7], v[6:7], v[10:11]
	v_pk_mul_f32 v[8:9], v[8:9], v[12:13]
	s_waitcnt vmcnt(2)
	v_pk_add_f32 v[10:11], v[20:21], v[16:17]
	v_pk_add_f32 v[12:13], v[18:19], v[14:15]
	s_waitcnt vmcnt(0)
	v_pk_add_f32 v[16:17], v[22:23], v[26:27]
	v_pk_add_f32 v[14:15], v[24:25], v[28:29]
	v_pk_add_f32 v[16:17], v[16:17], 1.0 op_sel_hi:[1,0]
	v_pk_add_f32 v[14:15], v[14:15], 1.0 op_sel_hi:[1,0]
	v_pk_fma_f32 v[6:7], v[6:7], v[16:17], v[12:13]
	v_pk_fma_f32 v[8:9], v[8:9], v[14:15], v[10:11]
	v_cvt_pk_bf16_f32 v6, v6, v7
	s_nop 0
	v_cvt_pk_bf16_f32 v7, v8, v9
	global_store_dwordx2 v[74:75], v[6:7], off offset:3072 nt
	global_load_dwordx4 v[6:9], v[68:69], off nt
	s_nop 0
	global_load_dwordx4 v[10:13], v[70:71], off nt
	global_load_dwordx4 v[14:17], v91, s[8:9] nt
	global_load_dwordx4 v[18:21], v91, s[10:11] nt
	global_load_dwordx4 v[22:25], v[72:73], off nt
	s_waitcnt vmcnt(4)
	v_pk_mul_f32 v[2:3], v[2:3], v[6:7]
	v_pk_mul_f32 v[4:5], v[4:5], v[8:9]
	s_waitcnt vmcnt(2)
	v_pk_add_f32 v[6:7], v[16:17], v[12:13]
	v_pk_add_f32 v[8:9], v[14:15], v[10:11]
	s_waitcnt vmcnt(0)
	v_pk_add_f32 v[12:13], v[18:19], v[22:23]
	v_pk_add_f32 v[10:11], v[20:21], v[24:25]
	v_pk_add_f32 v[12:13], v[12:13], 1.0 op_sel_hi:[1,0]
	v_pk_add_f32 v[10:11], v[10:11], 1.0 op_sel_hi:[1,0]
	v_pk_fma_f32 v[2:3], v[2:3], v[12:13], v[8:9]
	v_pk_fma_f32 v[4:5], v[4:5], v[10:11], v[6:7]
	v_cvt_pk_bf16_f32 v2, v2, v3
	s_nop 0
	v_cvt_pk_bf16_f32 v3, v4, v5
	global_store_dwordx2 v[74:75], v[2:3], off offset:3584 nt
	s_cbranch_scc0 .LBB0_188

.LBB0_893:
	s_cmp_gt_i32 s38, 32
	v_lshl_or_b32 v142, s12, 8, v165
	s_cselect_b32 s12, 0xc000, 0
	s_add_u32 s12, s30, s12
	v_ashrrev_i32_e32 v143, 31, v142
	s_addc_u32 s13, s31, 0
	v_lshlrev_b64 v[142:143], 2, v[142:143]
	v_lshl_add_u64 v[144:145], s[12:13], 0, v[142:143]
	v_lshl_add_u64 v[156:157], v[144:145], 0, s[10:11]
	v_add_co_u32_e32 v144, vcc, s59, v144
	v_lshl_add_u32 v171, s38, 8, v1
	s_nop 0
	v_addc_co_u32_e32 v145, vcc, 0, v145, vcc
	v_cmp_lt_i32_e32 vcc, s65, v171
	v_or_b32_e32 v177, 16, v171
	v_lshl_add_u64 v[158:159], s[6:7], 0, v[142:143]
	global_load_dwordx4 v[172:175], v[144:145], off nt
	global_load_dwordx4 v[178:181], v[158:159], off nt
	global_load_dwordx4 v[148:151], v[158:159], off offset:64 nt
	global_load_dwordx4 v[152:155], v[156:157], off offset:64 nt
	global_load_dwordx4 v[160:163], v[156:157], off offset:512 nt
	global_load_dwordx4 v[182:185], v[156:157], off offset:576 nt
	global_load_dwordx4 v[186:189], v[158:159], off offset:512 nt
	global_load_dwordx4 v[190:193], v[158:159], off offset:576 nt
	v_cndmask_b32_e32 v156, v169, v170, vcc
	v_cmp_lt_i32_e32 vcc, s65, v177
	v_add_u32_e32 v156, v156, v171
	v_ashrrev_i32_e32 v157, 31, v156
	v_cndmask_b32_e32 v206, v169, v170, vcc
	v_add_u32_e32 v206, v206, v177
	v_lshl_add_u64 v[144:145], s[36:37], 0, v[142:143]
	v_lshlrev_b64 v[156:157], 13, v[156:157]
	v_ashrrev_i32_e32 v207, 31, v206
	v_lshl_add_u64 v[158:159], v[144:145], 0, v[156:157]
	v_lshlrev_b64 v[226:227], 13, v[206:207]
	global_load_dwordx4 v[194:197], v[158:159], off offset:64 nt
	global_load_dwordx4 v[198:201], v[158:159], off offset:512 nt
	global_load_dwordx4 v[202:205], v[158:159], off offset:576 nt
	v_lshl_add_u64 v[222:223], v[144:145], 0, v[226:227]
	global_load_dwordx4 v[206:209], v[222:223], off offset:64 nt
	global_load_dwordx4 v[210:213], v[222:223], off offset:512 nt
	global_load_dwordx4 v[214:217], v[222:223], off offset:576 nt
	global_load_dwordx4 v[218:221], v[158:159], off nt
	s_nop 0
	global_load_dwordx4 v[222:225], v[222:223], off nt
	v_or_b32_e32 v158, 32, v171
	v_cmp_lt_i32_e32 vcc, s65, v158
	v_lshl_add_u64 v[156:157], s[28:29], 0, v[156:157]
	v_lshl_add_u64 v[230:231], v[156:157], 0, v[142:143]
	v_cndmask_b32_e32 v159, v169, v170, vcc
	v_add_u32_e32 v158, v159, v158
	v_ashrrev_i32_e32 v159, 31, v158
	v_lshl_add_u64 v[156:157], s[28:29], 0, v[226:227]
	v_lshlrev_b64 v[228:229], 13, v[158:159]
	v_lshl_add_u64 v[232:233], v[156:157], 0, v[142:143]
	v_lshl_add_u64 v[226:227], v[144:145], 0, v[228:229]
	s_waitcnt vmcnt(0)
	v_pk_add_f32 v[156:157], v[154:155], v[150:151]
	v_pk_add_f32 v[158:159], v[152:153], v[148:149]
	v_pk_add_f32 v[152:153], v[162:163], v[188:189]
	v_pk_add_f32 v[150:151], v[182:183], v[190:191]
	v_pk_add_f32 v[154:155], v[160:161], v[186:187]
	v_pk_add_f32 v[148:149], v[184:185], v[192:193]
	v_pk_add_f32 v[162:163], v[172:173], v[178:179]
	v_pk_add_f32 v[160:161], v[174:175], v[180:181]
	v_lshl_add_u64 v[180:181], s[28:29], 0, v[228:229]
	v_lshl_add_u64 v[180:181], v[180:181], 0, v[142:143]
	v_pk_fma_f32 v[128:129], v[128:129], v[156:157], v[196:197]
	v_pk_fma_f32 v[126:127], v[126:127], v[158:159], v[194:195]
	v_pk_fma_f32 v[106:107], v[106:107], v[150:151], v[202:203]
	v_pk_fma_f32 v[112:113], v[112:113], v[152:153], v[200:201]
	v_pk_fma_f32 v[110:111], v[110:111], v[154:155], v[198:199]
	v_pk_fma_f32 v[108:109], v[108:109], v[148:149], v[204:205]
	global_store_dwordx4 v[230:231], v[126:129], off offset:64 nt
	global_store_dwordx4 v[230:231], v[110:113], off offset:512 nt
	global_store_dwordx4 v[230:231], v[106:109], off offset:576 nt
	v_pk_fma_f32 v[120:121], v[120:121], v[156:157], v[208:209]
	v_pk_fma_f32 v[118:119], v[118:119], v[158:159], v[206:207]
	v_pk_fma_f32 v[106:107], v[114:115], v[162:163], v[222:223]
	v_or_b32_e32 v114, 48, v171
	v_cmp_lt_i32_e32 vcc, s65, v114
	v_pk_fma_f32 v[104:105], v[104:105], v[152:153], v[212:213]
	v_pk_fma_f32 v[102:103], v[102:103], v[154:155], v[210:211]
	v_cndmask_b32_e32 v115, v169, v170, vcc
	v_add_u32_e32 v114, v115, v114
	v_ashrrev_i32_e32 v115, 31, v114
	v_pk_fma_f32 v[100:101], v[100:101], v[148:149], v[216:217]
	v_pk_fma_f32 v[98:99], v[98:99], v[150:151], v[214:215]
	v_pk_fma_f32 v[124:125], v[124:125], v[160:161], v[220:221]
	v_pk_fma_f32 v[122:123], v[122:123], v[162:163], v[218:219]
	v_pk_fma_f32 v[108:109], v[116:117], v[160:161], v[224:225]
	global_store_dwordx4 v[232:233], v[118:121], off offset:64 nt
	global_store_dwordx4 v[232:233], v[102:105], off offset:512 nt
	global_store_dwordx4 v[232:233], v[98:101], off offset:576 nt
	global_store_dwordx4 v[230:231], v[122:125], off nt
	global_store_dwordx4 v[232:233], v[106:109], off nt
	v_lshlrev_b64 v[172:173], 13, v[114:115]
	v_lshl_add_u64 v[126:127], v[144:145], 0, v[172:173]
	global_load_dwordx4 v[98:101], v[226:227], off nt
	global_load_dwordx4 v[102:105], v[226:227], off offset:64 nt
	global_load_dwordx4 v[106:109], v[226:227], off offset:512 nt
	global_load_dwordx4 v[110:113], v[226:227], off offset:576 nt
	global_load_dwordx4 v[114:117], v[126:127], off nt
	global_load_dwordx4 v[118:121], v[126:127], off offset:64 nt
	global_load_dwordx4 v[122:125], v[126:127], off offset:512 nt
	s_nop 0
	global_load_dwordx4 v[126:129], v[126:127], off offset:576 nt
	v_cmp_lt_i32_e32 vcc, s66, v171
	v_lshl_add_u64 v[172:173], s[28:29], 0, v[172:173]
	v_lshl_add_u64 v[172:173], v[172:173], 0, v[142:143]
	v_cndmask_b32_e32 v174, v169, v170, vcc
	v_cmp_lt_i32_e32 vcc, s69, v171
	v_add3_u32 v174, v171, v174, s67
	v_ashrrev_i32_e32 v175, 31, v174
	v_cndmask_b32_e32 v177, v169, v170, vcc
	v_lshlrev_b64 v[174:175], 13, v[174:175]
	v_lshl_add_u64 v[178:179], v[144:145], 0, v[174:175]
	v_cmp_lt_i32_e32 vcc, s77, v171
	s_waitcnt vmcnt(7)
	v_pk_fma_f32 v[96:97], v[96:97], v[160:161], v[100:101]
	v_pk_fma_f32 v[94:95], v[94:95], v[162:163], v[98:99]
	s_waitcnt vmcnt(5)
	v_pk_fma_f32 v[78:79], v[78:79], v[154:155], v[106:107]
	v_pk_fma_f32 v[92:93], v[92:93], v[156:157], v[104:105]
	v_pk_fma_f32 v[90:91], v[90:91], v[158:159], v[102:103]
	v_pk_fma_f32 v[80:81], v[80:81], v[152:153], v[108:109]
	s_waitcnt vmcnt(4)
	v_pk_fma_f32 v[76:77], v[76:77], v[148:149], v[112:113]
	v_pk_fma_f32 v[74:75], v[74:75], v[150:151], v[110:111]
	s_waitcnt vmcnt(3)
	v_pk_fma_f32 v[88:89], v[88:89], v[160:161], v[116:117]
	v_pk_fma_f32 v[86:87], v[86:87], v[162:163], v[114:115]
	s_waitcnt vmcnt(2)
	v_pk_fma_f32 v[84:85], v[84:85], v[156:157], v[120:121]
	v_pk_fma_f32 v[82:83], v[82:83], v[158:159], v[118:119]
	s_waitcnt vmcnt(1)
	v_pk_fma_f32 v[72:73], v[72:73], v[152:153], v[124:125]
	v_pk_fma_f32 v[70:71], v[70:71], v[154:155], v[122:123]
	s_waitcnt vmcnt(0)
	v_pk_fma_f32 v[68:69], v[68:69], v[148:149], v[128:129]
	v_pk_fma_f32 v[66:67], v[66:67], v[150:151], v[126:127]
	global_store_dwordx4 v[180:181], v[94:97], off nt
	global_store_dwordx4 v[180:181], v[90:93], off offset:64 nt
	global_store_dwordx4 v[180:181], v[78:81], off offset:512 nt
	global_store_dwordx4 v[180:181], v[74:77], off offset:576 nt
	global_store_dwordx4 v[172:173], v[86:89], off nt
	global_store_dwordx4 v[172:173], v[82:85], off offset:64 nt
	global_store_dwordx4 v[172:173], v[70:73], off offset:512 nt
	global_store_dwordx4 v[172:173], v[66:69], off offset:576 nt
	v_add3_u32 v78, v171, v177, s76
	v_ashrrev_i32_e32 v79, 31, v78
	v_lshlrev_b64 v[98:99], 13, v[78:79]
	global_load_dwordx4 v[66:69], v[178:179], off nt
	global_load_dwordx4 v[70:73], v[178:179], off offset:64 nt
	global_load_dwordx4 v[74:77], v[178:179], off offset:512 nt
	global_load_dwordx4 v[78:81], v[178:179], off offset:576 nt
	v_lshl_add_u64 v[94:95], v[144:145], 0, v[98:99]
	global_load_dwordx4 v[82:85], v[94:95], off nt
	global_load_dwordx4 v[86:89], v[94:95], off offset:64 nt
	global_load_dwordx4 v[90:93], v[94:95], off offset:512 nt
	s_nop 0
	global_load_dwordx4 v[94:97], v[94:95], off offset:576 nt
	v_cndmask_b32_e32 v100, v169, v170, vcc
	v_cmp_lt_i32_e32 vcc, s79, v171
	v_lshl_add_u64 v[102:103], s[28:29], 0, v[174:175]
	v_add3_u32 v100, v171, v100, s78
	v_cndmask_b32_e32 v106, v169, v170, vcc
	v_lshl_add_u64 v[98:99], s[28:29], 0, v[98:99]
	v_lshl_add_u64 v[102:103], v[102:103], 0, v[142:143]
	v_ashrrev_i32_e32 v101, 31, v100
	v_lshl_add_u64 v[98:99], v[98:99], 0, v[142:143]
	v_lshlrev_b64 v[100:101], 13, v[100:101]
	v_lshl_add_u64 v[104:105], v[144:145], 0, v[100:101]
	s_andn2_b64 vcc, exec, s[2:3]
	s_mov_b64 s[2:3], -1
	s_waitcnt vmcnt(7)
	v_pk_fma_f32 v[64:65], v[64:65], v[160:161], v[68:69]
	v_pk_fma_f32 v[62:63], v[62:63], v[162:163], v[66:67]
	s_waitcnt vmcnt(5)
	v_pk_fma_f32 v[46:47], v[46:47], v[154:155], v[74:75]
	v_pk_fma_f32 v[60:61], v[60:61], v[156:157], v[72:73]
	v_pk_fma_f32 v[58:59], v[58:59], v[158:159], v[70:71]
	v_pk_fma_f32 v[48:49], v[48:49], v[152:153], v[76:77]
	s_waitcnt vmcnt(4)
	v_pk_fma_f32 v[44:45], v[44:45], v[148:149], v[80:81]
	v_pk_fma_f32 v[42:43], v[42:43], v[150:151], v[78:79]
	s_waitcnt vmcnt(3)
	v_pk_fma_f32 v[56:57], v[56:57], v[160:161], v[84:85]
	v_pk_fma_f32 v[54:55], v[54:55], v[162:163], v[82:83]
	s_waitcnt vmcnt(2)
	v_pk_fma_f32 v[52:53], v[52:53], v[156:157], v[88:89]
	v_pk_fma_f32 v[50:51], v[50:51], v[158:159], v[86:87]
	s_waitcnt vmcnt(1)
	v_pk_fma_f32 v[40:41], v[40:41], v[152:153], v[92:93]
	v_pk_fma_f32 v[38:39], v[38:39], v[154:155], v[90:91]
	s_waitcnt vmcnt(0)
	v_pk_fma_f32 v[36:37], v[36:37], v[148:149], v[96:97]
	v_pk_fma_f32 v[34:35], v[34:35], v[150:151], v[94:95]
	global_store_dwordx4 v[102:103], v[62:65], off nt
	global_store_dwordx4 v[102:103], v[58:61], off offset:64 nt
	global_store_dwordx4 v[102:103], v[46:49], off offset:512 nt
	global_store_dwordx4 v[102:103], v[42:45], off offset:576 nt
	global_store_dwordx4 v[98:99], v[54:57], off nt
	global_store_dwordx4 v[98:99], v[50:53], off offset:64 nt
	global_store_dwordx4 v[98:99], v[38:41], off offset:512 nt
	global_store_dwordx4 v[98:99], v[34:37], off offset:576 nt
	v_add3_u32 v46, v171, v106, s80
	v_ashrrev_i32_e32 v47, 31, v46
	v_lshlrev_b64 v[66:67], 13, v[46:47]
	global_load_dwordx4 v[34:37], v[104:105], off nt
	global_load_dwordx4 v[38:41], v[104:105], off offset:64 nt
	v_lshl_add_u64 v[62:63], v[144:145], 0, v[66:67]
	global_load_dwordx4 v[42:45], v[104:105], off offset:512 nt
	global_load_dwordx4 v[46:49], v[104:105], off offset:576 nt
	global_load_dwordx4 v[50:53], v[62:63], off nt
	global_load_dwordx4 v[54:57], v[62:63], off offset:64 nt
	global_load_dwordx4 v[58:61], v[62:63], off offset:512 nt
	s_nop 0
	global_load_dwordx4 v[62:65], v[62:63], off offset:576 nt
	v_lshl_add_u64 v[68:69], s[28:29], 0, v[100:101]
	v_lshl_add_u64 v[66:67], s[28:29], 0, v[66:67]
	v_lshl_add_u64 v[68:69], v[68:69], 0, v[142:143]
	v_lshl_add_u64 v[66:67], v[66:67], 0, v[142:143]
	s_waitcnt vmcnt(7)
	v_pk_fma_f32 v[32:33], v[32:33], v[160:161], v[36:37]
	v_pk_fma_f32 v[30:31], v[30:31], v[162:163], v[34:35]
	s_waitcnt vmcnt(6)
	v_pk_fma_f32 v[28:29], v[28:29], v[156:157], v[40:41]
	v_pk_fma_f32 v[26:27], v[26:27], v[158:159], v[38:39]
	s_waitcnt vmcnt(5)
	v_pk_fma_f32 v[16:17], v[16:17], v[152:153], v[44:45]
	v_pk_fma_f32 v[14:15], v[14:15], v[154:155], v[42:43]
	s_waitcnt vmcnt(4)
	v_pk_fma_f32 v[12:13], v[12:13], v[148:149], v[48:49]
	v_pk_fma_f32 v[10:11], v[10:11], v[150:151], v[46:47]
	s_waitcnt vmcnt(3)
	v_pk_fma_f32 v[24:25], v[24:25], v[160:161], v[52:53]
	v_pk_fma_f32 v[22:23], v[22:23], v[162:163], v[50:51]
	s_waitcnt vmcnt(2)
	v_pk_fma_f32 v[20:21], v[20:21], v[156:157], v[56:57]
	v_pk_fma_f32 v[18:19], v[18:19], v[158:159], v[54:55]
	s_waitcnt vmcnt(1)
	v_pk_fma_f32 v[8:9], v[8:9], v[152:153], v[60:61]
	v_pk_fma_f32 v[6:7], v[6:7], v[154:155], v[58:59]
	s_waitcnt vmcnt(0)
	v_pk_fma_f32 v[4:5], v[4:5], v[148:149], v[64:65]
	v_pk_fma_f32 v[2:3], v[2:3], v[150:151], v[62:63]
	global_store_dwordx4 v[68:69], v[30:33], off nt
	global_store_dwordx4 v[68:69], v[26:29], off offset:64 nt
	global_store_dwordx4 v[68:69], v[14:17], off offset:512 nt
	global_store_dwordx4 v[68:69], v[10:13], off offset:576 nt
	global_store_dwordx4 v[66:67], v[22:25], off nt
	global_store_dwordx4 v[66:67], v[18:21], off offset:64 nt
	global_store_dwordx4 v[66:67], v[6:9], off offset:512 nt
	global_store_dwordx4 v[66:67], v[2:5], off offset:576 nt
	s_cbranch_vccnz .LBB0_882
	s_andn2_b64 vcc, exec, s[4:5]
	s_cbranch_vccnz .LBB0_881
	s_barrier
	s_branch .LBB0_881

.LBB0_966:
	global_load_dwordx4 v[14:17], v[66:67], off offset:-3072 nt
	global_load_dwordx4 v[18:21], v[66:67], off offset:-4096 nt
	global_load_dwordx4 v[10:13], v[66:67], off offset:-2048 nt
	s_ashr_i32 s0, s12, 13
	v_add_co_u32_e32 v68, vcc, s10, v66
	global_load_dwordx4 v[2:5], v[66:67], off nt
	s_lshl_b32 s1, s0, 8
	s_mulk_i32 s0, 0x3000
	v_addc_co_u32_e32 v69, vcc, -1, v67, vcc
	global_load_dwordx4 v[6:9], v[66:67], off offset:-1024 nt
	global_load_dwordx4 v[86:89], v[24:25], off nt
	global_load_dwordx4 v[90:93], v[26:27], off nt
	global_load_dwordx4 v[94:97], v[28:29], off nt
	global_load_dwordx4 v[98:101], v[68:69], off offset:-3072 nt
	global_load_dwordx4 v[102:105], v[68:69], off offset:-2048 nt
	global_load_dwordx4 v[106:109], v[68:69], off offset:-1024 nt
	s_add_i32 s6, s12, s1
	s_ashr_i32 s1, s0, 31
	s_addk_i32 s6, 0x100
	s_lshl_b64 s[0:1], s[0:1], 2
	s_add_u32 s8, s30, s0
	s_addc_u32 s9, s31, s1
	s_ashr_i32 s7, s6, 31
	s_lshl_b64 s[0:1], s[6:7], 12
	s_add_u32 s6, s8, 0x6000
	s_addc_u32 s7, s9, 0
	global_load_dwordx4 v[110:113], v78, s[6:7] nt
	s_add_u32 s8, s8, 0x8000
	s_addc_u32 s9, s9, 0
	global_load_dwordx4 v[114:117], v78, s[8:9] nt
	v_lshl_add_u64 v[68:69], v[22:23], 0, s[0:1]
	s_add_i32 s12, s12, s68
	v_lshl_add_u64 v[66:67], v[66:67], 0, s[4:5]
	s_cmpk_lt_i32 s12, 0x4000
	s_waitcnt vmcnt(0)
	v_mul_f32_e32 v144, v16, v16
	v_mul_f32_e32 v70, v19, v19
	v_pk_mul_f32 v[120:121], v[12:13], v[12:13]
	v_pk_mul_f32 v[122:123], v[10:11], v[10:11]
	v_mul_f32_e32 v118, v21, v21
	v_pk_mov_b32 v[130:131], v[122:123], v[120:121] op_sel:[1,0]
	v_mul_f32_e32 v150, v4, v4
	v_mul_f32_e32 v151, v5, v5
	v_mul_f32_e32 v124, v7, v7
	v_mul_f32_e32 v126, v9, v9
	v_mov_b32_e32 v123, v121
	v_pk_fma_f32 v[120:121], v[6:7], v[6:7], v[124:125] op_sel_hi:[1,1,0]
	v_pk_fma_f32 v[124:125], v[8:9], v[8:9], v[126:127] op_sel_hi:[1,1,0]
	v_mov_b32_e32 v132, v99
	v_mov_b32_e32 v133, v103
	v_mov_b32_e32 v136, v101
	v_mov_b32_e32 v137, v105
	v_mul_f32_e32 v145, v17, v17
	v_pk_fma_f32 v[128:129], v[18:19], v[18:19], v[70:71] op_sel_hi:[1,1,0]
	v_pk_fma_f32 v[118:119], v[20:21], v[20:21], v[118:119] op_sel_hi:[1,1,0]
	v_mov_b32_e32 v126, v98
	v_mov_b32_e32 v127, v102
	v_mov_b32_e32 v134, v100
	v_mov_b32_e32 v135, v104
	v_pk_mul_f32 v[138:139], v[108:109], v[108:109]
	v_pk_mul_f32 v[140:141], v[106:107], v[106:107]
	v_pk_add_f32 v[122:123], v[130:131], v[122:123]
	v_mov_b32_e32 v121, v150
	v_mov_b32_e32 v125, v151
	v_pk_mul_f32 v[130:131], v[132:133], v[132:133]
	v_pk_mul_f32 v[132:133], v[136:137], v[136:137]
	v_mov_b32_e32 v129, v144
	v_mov_b32_e32 v119, v145
	v_pk_mov_b32 v[136:137], v[140:141], v[138:139] op_sel:[1,0]
	v_mov_b32_e32 v141, v139
	v_pk_add_f32 v[120:121], v[120:121], v[124:125]
	v_pk_fma_f32 v[124:125], v[126:127], v[126:127], v[130:131]
	v_pk_fma_f32 v[126:127], v[134:135], v[134:135], v[132:133]
	v_pk_add_f32 v[118:119], v[128:129], v[118:119]
	v_pk_add_f32 v[128:129], v[136:137], v[140:141]
	v_pk_add_f32 v[124:125], v[124:125], v[126:127]
	v_mul_f32_e32 v142, v14, v14
	v_mul_f32_e32 v143, v15, v15
	v_pk_add_f32 v[126:127], v[128:129], v[128:129] op_sel:[0,1] op_sel_hi:[1,0]
	v_pk_add_f32 v[124:125], v[124:125], v[124:125] op_sel:[0,1] op_sel_hi:[1,0]
	v_mov_b32_e32 v127, v143
	v_mov_b32_e32 v125, v142
	v_pk_add_f32 v[124:125], v[124:125], v[126:127]
	v_mul_f32_e32 v148, v2, v2
	v_pk_add_f32 v[118:119], v[124:125], v[118:119]
	v_mul_f32_e32 v149, v3, v3
	v_pk_add_f32 v[122:123], v[122:123], v[122:123] op_sel:[0,1] op_sel_hi:[1,0]
	v_pk_add_f32 v[90:91], v[110:111], v[90:91]
	v_pk_add_f32 v[110:111], v[118:119], v[118:119] op_sel:[0,1] op_sel_hi:[1,0]
	v_mov_b32_e32 v123, v149
	v_mov_b32_e32 v111, v148
	v_pk_add_f32 v[110:111], v[110:111], v[122:123]
	v_pk_add_f32 v[92:93], v[112:113], v[92:93]
	v_pk_add_f32 v[110:111], v[110:111], v[120:121]
	v_pk_add_f32 v[94:95], v[114:115], v[94:95]
	v_add_f32_e32 v70, v110, v111
	ds_bpermute_b32 v110, v1, v70
	v_pk_add_f32 v[96:97], v[116:117], v[96:97]
	v_pk_add_f32 v[94:95], v[94:95], 1.0 op_sel_hi:[1,0]
	v_pk_add_f32 v[96:97], v[96:97], 1.0 op_sel_hi:[1,0]
	s_waitcnt lgkmcnt(0)
	v_add_f32_e32 v70, v70, v110
	ds_bpermute_b32 v110, v71, v70
	s_waitcnt lgkmcnt(0)
	v_add_f32_e32 v70, v70, v110
	ds_bpermute_b32 v110, v72, v70
	s_waitcnt lgkmcnt(0)
	v_add_f32_e32 v70, v70, v110
	ds_bpermute_b32 v110, v73, v70
	s_waitcnt lgkmcnt(0)
	v_add_f32_e32 v70, v70, v110
	ds_bpermute_b32 v110, v74, v70
	s_waitcnt lgkmcnt(0)
	v_add_f32_e32 v70, v70, v110
	ds_bpermute_b32 v110, v75, v70
	s_waitcnt lgkmcnt(0)
	v_add_f32_e32 v70, v70, v110
	v_fmamk_f32 v70, v70, 0x3a000000, v76
	v_mul_f32_e32 v110, 0x4f800000, v70
	v_cmp_gt_f32_e32 vcc, s11, v70
	s_nop 1
	v_cndmask_b32_e32 v70, v70, v110, vcc
	v_sqrt_f32_e32 v110, v70
	s_nop 0
	v_add_u32_e32 v111, -1, v110
	v_add_u32_e32 v112, 1, v110
	v_fma_f32 v113, -v111, v110, v70
	v_fma_f32 v114, -v112, v110, v70
	v_cmp_ge_f32_e64 s[0:1], 0, v113
	s_nop 1
	v_cndmask_b32_e64 v110, v110, v111, s[0:1]
	v_cmp_lt_f32_e64 s[0:1], 0, v114
	s_nop 1
	v_cndmask_b32_e64 v110, v110, v112, s[0:1]
	v_mul_f32_e32 v111, 0x37800000, v110
	v_cndmask_b32_e32 v110, v110, v111, vcc
	v_cmp_class_f32_e32 vcc, v70, v77
	s_nop 1
	v_cndmask_b32_e32 v70, v110, v70, vcc
	v_div_scale_f32 v110, s[0:1], v70, v70, 1.0
	v_rcp_f32_e32 v112, v110
	v_div_scale_f32 v111, vcc, 1.0, v70, 1.0
	v_fma_f32 v113, -v110, v112, 1.0
	v_fmac_f32_e32 v112, v113, v112
	v_mul_f32_e32 v113, v111, v112
	v_fma_f32 v114, -v110, v113, v111
	v_fmac_f32_e32 v113, v114, v112
	v_fma_f32 v110, -v110, v113, v111
	v_div_fmas_f32 v110, v110, v112, v113
	v_div_fixup_f32 v70, v110, v70, 1.0
	v_pk_mul_f32 v[98:99], v[98:99], v[70:71] op_sel_hi:[1,0]
	v_pk_mul_f32 v[100:101], v[100:101], v[70:71] op_sel_hi:[1,0]
	v_pk_mul_f32 v[86:87], v[86:87], v[98:99]
	v_pk_mul_f32 v[88:89], v[88:89], v[100:101]
	v_pk_fma_f32 v[86:87], v[94:95], v[86:87], v[90:91]
	v_pk_fma_f32 v[88:89], v[96:97], v[88:89], v[92:93]
	v_cvt_pk_bf16_f32 v86, v86, v87
	v_pk_mul_f32 v[110:111], v[104:105], v[70:71] op_sel_hi:[1,0]
	v_cvt_pk_bf16_f32 v87, v88, v89
	global_store_dwordx2 v[68:69], v[86:87], off nt
	v_pk_mul_f32 v[112:113], v[102:103], v[70:71] op_sel_hi:[1,0]
	global_load_dwordx4 v[86:89], v[24:25], off offset:1024 nt
	global_load_dwordx4 v[90:93], v[30:31], off nt
	global_load_dwordx4 v[94:97], v79, s[6:7] nt
	global_load_dwordx4 v[98:101], v79, s[8:9] nt
	global_load_dwordx4 v[102:105], v[32:33], off nt
	v_pk_mul_f32 v[106:107], v[106:107], v[70:71] op_sel_hi:[1,0]
	v_pk_mul_f32 v[108:109], v[108:109], v[70:71] op_sel_hi:[1,0]
	v_pk_mul_f32 v[18:19], v[18:19], v[70:71] op_sel_hi:[1,0]
	v_pk_mul_f32 v[20:21], v[20:21], v[70:71] op_sel_hi:[1,0]
	v_pk_mul_f32 v[14:15], v[14:15], v[70:71] op_sel_hi:[1,0]
	v_pk_mul_f32 v[16:17], v[16:17], v[70:71] op_sel_hi:[1,0]
	v_pk_mul_f32 v[10:11], v[10:11], v[70:71] op_sel_hi:[1,0]
	v_pk_mul_f32 v[12:13], v[12:13], v[70:71] op_sel_hi:[1,0]
	v_pk_mul_f32 v[6:7], v[6:7], v[70:71] op_sel_hi:[1,0]
	v_pk_mul_f32 v[8:9], v[8:9], v[70:71] op_sel_hi:[1,0]
	v_pk_mul_f32 v[2:3], v[2:3], v[70:71] op_sel_hi:[1,0]
	v_pk_mul_f32 v[4:5], v[4:5], v[70:71] op_sel_hi:[1,0]
	s_waitcnt vmcnt(4)
	v_pk_mul_f32 v[86:87], v[86:87], v[112:113]
	v_pk_mul_f32 v[88:89], v[88:89], v[110:111]
	s_waitcnt vmcnt(2)
	v_pk_add_f32 v[92:93], v[96:97], v[92:93]
	v_pk_add_f32 v[90:91], v[94:95], v[90:91]
	s_waitcnt vmcnt(0)
	v_pk_add_f32 v[96:97], v[98:99], v[102:103]
	v_pk_add_f32 v[94:95], v[100:101], v[104:105]
	v_pk_add_f32 v[96:97], v[96:97], 1.0 op_sel_hi:[1,0]
	v_pk_add_f32 v[94:95], v[94:95], 1.0 op_sel_hi:[1,0]
	v_pk_fma_f32 v[86:87], v[86:87], v[96:97], v[90:91]
	v_pk_fma_f32 v[88:89], v[88:89], v[94:95], v[92:93]
	v_cvt_pk_bf16_f32 v86, v86, v87
	s_nop 0
	v_cvt_pk_bf16_f32 v87, v88, v89
	global_store_dwordx2 v[68:69], v[86:87], off offset:512 nt
	global_load_dwordx4 v[86:89], v80, s[6:7] nt
	s_nop 0
	global_load_dwordx4 v[90:93], v80, s[8:9] nt
	global_load_dwordx4 v[94:97], v[34:35], off nt
	global_load_dwordx4 v[98:101], v[36:37], off nt
	global_load_dwordx4 v[102:105], v[24:25], off offset:2048 nt
	s_waitcnt vmcnt(2)
	v_pk_add_f32 v[86:87], v[86:87], v[94:95]
	s_waitcnt vmcnt(1)
	v_pk_add_f32 v[90:91], v[90:91], v[98:99]
	s_waitcnt vmcnt(0)
	v_pk_mul_f32 v[102:103], v[106:107], v[102:103]
	v_pk_add_f32 v[92:93], v[92:93], v[100:101]
	v_pk_add_f32 v[90:91], v[90:91], 1.0 op_sel_hi:[1,0]
	v_pk_mul_f32 v[104:105], v[108:109], v[104:105]
	v_pk_add_f32 v[88:89], v[88:89], v[96:97]
	v_pk_add_f32 v[92:93], v[92:93], 1.0 op_sel_hi:[1,0]
	v_pk_fma_f32 v[86:87], v[102:103], v[90:91], v[86:87]
	v_pk_fma_f32 v[88:89], v[104:105], v[92:93], v[88:89]
	v_cvt_pk_bf16_f32 v86, v86, v87
	s_nop 0
	v_cvt_pk_bf16_f32 v87, v88, v89
	global_store_dwordx2 v[68:69], v[86:87], off offset:1024 nt
	global_load_dwordx4 v[86:89], v81, s[6:7] nt
	s_nop 0
	global_load_dwordx4 v[90:93], v81, s[8:9] nt
	global_load_dwordx4 v[94:97], v[38:39], off nt
	global_load_dwordx4 v[98:101], v[40:41], off nt
	global_load_dwordx4 v[102:105], v[24:25], off offset:3072 nt
	s_waitcnt vmcnt(2)
	v_pk_add_f32 v[86:87], v[86:87], v[94:95]
	s_waitcnt vmcnt(1)
	v_pk_add_f32 v[90:91], v[90:91], v[98:99]
	s_waitcnt vmcnt(0)
	v_pk_mul_f32 v[18:19], v[18:19], v[102:103]
	v_pk_add_f32 v[92:93], v[92:93], v[100:101]
	v_pk_add_f32 v[90:91], v[90:91], 1.0 op_sel_hi:[1,0]
	v_pk_mul_f32 v[20:21], v[20:21], v[104:105]
	v_pk_add_f32 v[88:89], v[88:89], v[96:97]
	v_pk_add_f32 v[92:93], v[92:93], 1.0 op_sel_hi:[1,0]
	v_pk_fma_f32 v[18:19], v[18:19], v[90:91], v[86:87]
	v_pk_fma_f32 v[20:21], v[20:21], v[92:93], v[88:89]
	v_cvt_pk_bf16_f32 v18, v18, v19
	s_nop 0
	v_cvt_pk_bf16_f32 v19, v20, v21
	global_store_dwordx2 v[68:69], v[18:19], off offset:1536 nt
	global_load_dwordx4 v[18:21], v82, s[6:7] nt
	s_nop 0
	global_load_dwordx4 v[86:89], v82, s[8:9] nt
	global_load_dwordx4 v[90:93], v[44:45], off nt
	global_load_dwordx4 v[94:97], v[46:47], off nt
	global_load_dwordx4 v[98:101], v[42:43], off nt
	s_waitcnt vmcnt(2)
	v_pk_add_f32 v[18:19], v[18:19], v[90:91]
	s_waitcnt vmcnt(1)
	v_pk_add_f32 v[86:87], v[86:87], v[94:95]
	s_waitcnt vmcnt(0)
	v_pk_mul_f32 v[14:15], v[14:15], v[98:99]
	v_pk_add_f32 v[88:89], v[88:89], v[96:97]
	v_pk_add_f32 v[86:87], v[86:87], 1.0 op_sel_hi:[1,0]
	v_pk_mul_f32 v[16:17], v[16:17], v[100:101]
	v_pk_add_f32 v[20:21], v[20:21], v[92:93]
	v_pk_add_f32 v[88:89], v[88:89], 1.0 op_sel_hi:[1,0]
	v_pk_fma_f32 v[14:15], v[14:15], v[86:87], v[18:19]
	v_pk_fma_f32 v[16:17], v[16:17], v[88:89], v[20:21]
	v_cvt_pk_bf16_f32 v14, v14, v15
	s_nop 0
	v_cvt_pk_bf16_f32 v15, v16, v17
	global_store_dwordx2 v[68:69], v[14:15], off offset:2048 nt
	global_load_dwordx4 v[14:17], v83, s[6:7] nt
	s_nop 0
	global_load_dwordx4 v[18:21], v83, s[8:9] nt
	global_load_dwordx4 v[86:89], v[50:51], off nt
	global_load_dwordx4 v[90:93], v[52:53], off nt
	global_load_dwordx4 v[94:97], v[48:49], off nt
	s_waitcnt vmcnt(2)
	v_pk_add_f32 v[14:15], v[14:15], v[86:87]
	s_waitcnt vmcnt(1)
	v_pk_add_f32 v[18:19], v[18:19], v[90:91]
	s_waitcnt vmcnt(0)
	v_pk_mul_f32 v[10:11], v[10:11], v[94:95]
	v_pk_add_f32 v[20:21], v[20:21], v[92:93]
	v_pk_add_f32 v[18:19], v[18:19], 1.0 op_sel_hi:[1,0]
	v_pk_mul_f32 v[12:13], v[12:13], v[96:97]
	v_pk_add_f32 v[16:17], v[16:17], v[88:89]
	v_pk_add_f32 v[20:21], v[20:21], 1.0 op_sel_hi:[1,0]
	v_pk_fma_f32 v[10:11], v[10:11], v[18:19], v[14:15]
	v_pk_fma_f32 v[12:13], v[12:13], v[20:21], v[16:17]
	v_cvt_pk_bf16_f32 v10, v10, v11
	s_nop 0
	v_cvt_pk_bf16_f32 v11, v12, v13
	global_store_dwordx2 v[68:69], v[10:11], off offset:2560 nt
	global_load_dwordx4 v[10:13], v84, s[6:7] nt
	s_nop 0
	global_load_dwordx4 v[14:17], v84, s[8:9] nt
	global_load_dwordx4 v[18:21], v[56:57], off nt
	global_load_dwordx4 v[86:89], v[58:59], off nt
	global_load_dwordx4 v[90:93], v[54:55], off nt
	s_waitcnt vmcnt(2)
	v_pk_add_f32 v[10:11], v[10:11], v[18:19]
	s_waitcnt vmcnt(1)
	v_pk_add_f32 v[14:15], v[14:15], v[86:87]
	s_waitcnt vmcnt(0)
	v_pk_mul_f32 v[6:7], v[6:7], v[90:91]
	v_pk_add_f32 v[16:17], v[16:17], v[88:89]
	v_pk_add_f32 v[14:15], v[14:15], 1.0 op_sel_hi:[1,0]
	v_pk_mul_f32 v[8:9], v[8:9], v[92:93]
	v_pk_add_f32 v[12:13], v[12:13], v[20:21]
	v_pk_add_f32 v[16:17], v[16:17], 1.0 op_sel_hi:[1,0]
	v_pk_fma_f32 v[6:7], v[6:7], v[14:15], v[10:11]
	v_pk_fma_f32 v[8:9], v[8:9], v[16:17], v[12:13]
	v_cvt_pk_bf16_f32 v6, v6, v7
	s_nop 0
	v_cvt_pk_bf16_f32 v7, v8, v9
	global_store_dwordx2 v[68:69], v[6:7], off offset:3072 nt
	global_load_dwordx4 v[6:9], v85, s[6:7] nt
	s_nop 0
	global_load_dwordx4 v[10:13], v85, s[8:9] nt
	global_load_dwordx4 v[14:17], v[62:63], off nt
	global_load_dwordx4 v[18:21], v[64:65], off nt
	global_load_dwordx4 v[86:89], v[60:61], off nt
	s_waitcnt vmcnt(2)
	v_pk_add_f32 v[6:7], v[6:7], v[14:15]
	s_waitcnt vmcnt(1)
	v_pk_add_f32 v[10:11], v[10:11], v[18:19]
	s_waitcnt vmcnt(0)
	v_pk_mul_f32 v[2:3], v[2:3], v[86:87]
	v_pk_add_f32 v[12:13], v[12:13], v[20:21]
	v_pk_add_f32 v[10:11], v[10:11], 1.0 op_sel_hi:[1,0]
	v_pk_mul_f32 v[4:5], v[4:5], v[88:89]
	v_pk_add_f32 v[8:9], v[8:9], v[16:17]
	v_pk_add_f32 v[12:13], v[12:13], 1.0 op_sel_hi:[1,0]
	v_pk_fma_f32 v[2:3], v[2:3], v[10:11], v[6:7]
	v_pk_fma_f32 v[4:5], v[4:5], v[12:13], v[8:9]
	v_cvt_pk_bf16_f32 v2, v2, v3
	s_nop 0
	v_cvt_pk_bf16_f32 v3, v4, v5
	global_store_dwordx2 v[68:69], v[2:3], off offset:3584 nt
	s_cbranch_scc1 .LBB0_966

.LBB0_1046:
	v_mul_f32_e32 v154, 0xbfb8aa3b, v126
	v_exp_f32_e32 v155, v154
	v_mul_f32_e32 v154, 0xbfb8aa3b, v127
	v_exp_f32_e32 v156, v154
	v_lshl_or_b32 v154, s12, 7, v149
	v_add_f32_e32 v155, 1.0, v155
	v_rcp_f32_e32 v157, v155
	v_add_f32_e32 v155, 1.0, v156
	v_rcp_f32_e32 v156, v155
	v_lshl_add_u32 v153, s24, 8, v1
	v_mul_f32_e32 v126, v126, v157
	v_mul_f32_e32 v126, v126, v118
	v_mul_f32_e32 v118, v127, v156
	v_mul_f32_e32 v127, 0xbfb8aa3b, v128
	v_exp_f32_e32 v127, v127
	v_mul_f32_e32 v156, 0xbfb8aa3b, v129
	v_exp_f32_e32 v156, v156
	v_mul_f32_e32 v157, v118, v119
	v_add_f32_e32 v118, 1.0, v127
	v_rcp_f32_e32 v118, v118
	v_add_f32_e32 v119, 1.0, v156
	v_mul_f32_e32 v127, 0xbfb8aa3b, v122
	v_rcp_f32_e32 v119, v119
	v_exp_f32_e32 v127, v127
	v_mul_f32_e32 v118, v128, v118
	v_mul_f32_e32 v120, v118, v120
	v_mul_f32_e32 v118, v129, v119
	v_add_f32_e32 v119, 1.0, v127
	v_rcp_f32_e32 v119, v119
	v_mul_f32_e32 v127, 0xbfb8aa3b, v123
	v_mul_f32_e32 v121, v118, v121
	v_exp_f32_e32 v127, v127
	v_mul_f32_e32 v118, v122, v119
	v_mul_f32_e32 v128, v118, v114
	v_mul_f32_e32 v118, 0xbfb8aa3b, v124
	v_exp_f32_e32 v118, v118
	v_mul_f32_e32 v119, 0xbfb8aa3b, v125
	v_exp_f32_e32 v119, v119
	v_add_f32_e32 v114, 1.0, v127
	v_rcp_f32_e32 v114, v114
	v_add_f32_e32 v118, 1.0, v118
	v_rcp_f32_e32 v118, v118
	v_add_f32_e32 v119, 1.0, v119
	v_rcp_f32_e32 v119, v119
	v_mul_f32_e32 v114, v123, v114
	v_mul_f32_e32 v127, v114, v115
	v_mul_f32_e32 v114, v124, v118
	v_mul_f32_e32 v124, v114, v116
	v_mul_f32_e32 v114, v125, v119
	v_ashrrev_i32_e32 v155, 31, v154
	v_mul_f32_e32 v125, v114, v117
	v_mov_b64_e32 v[114:115], s[6:7]
	v_mad_i64_i32 v[118:119], s[12:13], v153, s59, v[114:115]
	v_lshlrev_b64 v[116:117], 1, v[154:155]
	v_lshl_add_u64 v[122:123], v[118:119], 0, v[116:117]
	v_cvt_pk_bf16_f32 v118, v126, v157
	v_cvt_pk_bf16_f32 v119, v120, v121
	v_mul_f32_e32 v121, 0xbfb8aa3b, v110
	v_exp_f32_e32 v126, v121
	v_mul_f32_e32 v121, 0xbfb8aa3b, v111
	v_cvt_pk_bf16_f32 v120, v128, v127
	v_exp_f32_e32 v127, v121
	v_cvt_pk_bf16_f32 v121, v124, v125
	v_add_f32_e32 v124, 1.0, v126
	v_rcp_f32_e32 v124, v124
	v_add_f32_e32 v125, 1.0, v127
	v_rcp_f32_e32 v125, v125
	global_store_dwordx4 v[122:123], v[118:121], off nt
	v_mul_f32_e32 v110, v110, v124
	v_mul_f32_e32 v110, v110, v102
	v_mul_f32_e32 v102, v111, v125
	v_mul_f32_e32 v111, 0xbfb8aa3b, v112
	v_exp_f32_e32 v111, v111
	v_mul_f32_e32 v118, 0xbfb8aa3b, v113
	v_exp_f32_e32 v118, v118
	v_mul_f32_e32 v119, v102, v103
	v_add_f32_e32 v102, 1.0, v111
	v_rcp_f32_e32 v102, v102
	v_add_f32_e32 v103, 1.0, v118
	v_mul_f32_e32 v111, 0xbfb8aa3b, v106
	v_rcp_f32_e32 v103, v103
	v_exp_f32_e32 v111, v111
	v_mul_f32_e32 v102, v112, v102
	v_mul_f32_e32 v104, v102, v104
	v_mul_f32_e32 v102, v113, v103
	v_add_f32_e32 v103, 1.0, v111
	v_rcp_f32_e32 v103, v103
	v_mul_f32_e32 v111, 0xbfb8aa3b, v107
	v_mul_f32_e32 v105, v102, v105
	v_exp_f32_e32 v111, v111
	v_mul_f32_e32 v102, v106, v103
	v_mul_f32_e32 v106, v102, v98
	v_mul_f32_e32 v102, 0xbfb8aa3b, v108
	v_exp_f32_e32 v102, v102
	v_mul_f32_e32 v103, 0xbfb8aa3b, v109
	v_exp_f32_e32 v103, v103
	v_add_f32_e32 v98, 1.0, v111
	v_rcp_f32_e32 v98, v98
	v_add_f32_e32 v102, 1.0, v102
	v_rcp_f32_e32 v102, v102
	v_add_f32_e32 v103, 1.0, v103
	v_rcp_f32_e32 v103, v103
	v_mul_f32_e32 v98, v107, v98
	v_mul_f32_e32 v107, v98, v99
	v_mul_f32_e32 v98, v108, v102
	v_mul_f32_e32 v108, v98, v100
	v_mul_f32_e32 v98, v109, v103
	v_mul_f32_e32 v101, v98, v101
	v_or_b32_e32 v98, 16, v153
	v_mad_i64_i32 v[98:99], s[12:13], v98, s59, v[114:115]
	v_lshl_add_u64 v[102:103], v[98:99], 0, v[116:117]
	v_cvt_pk_bf16_f32 v98, v110, v119
	v_cvt_pk_bf16_f32 v99, v104, v105
	v_mul_f32_e32 v104, 0xbfb8aa3b, v94
	v_exp_f32_e32 v104, v104
	v_mul_f32_e32 v105, 0xbfb8aa3b, v95
	v_exp_f32_e32 v105, v105
	v_cvt_pk_bf16_f32 v100, v106, v107
	v_add_f32_e32 v104, 1.0, v104
	v_rcp_f32_e32 v104, v104
	v_add_f32_e32 v105, 1.0, v105
	v_rcp_f32_e32 v105, v105
	v_cvt_pk_bf16_f32 v101, v108, v101
	v_mul_f32_e32 v94, v94, v104
	v_mul_f32_e32 v94, v94, v86
	v_mul_f32_e32 v86, v95, v105
	v_mul_f32_e32 v95, 0xbfb8aa3b, v96
	global_store_dwordx4 v[102:103], v[98:101], off nt
	v_exp_f32_e32 v95, v95
	s_andn2_b64 vcc, exec, s[2:3]
	v_mul_f32_e32 v98, 0xbfb8aa3b, v97
	v_exp_f32_e32 v98, v98
	v_mul_f32_e32 v99, v86, v87
	v_add_f32_e32 v86, 1.0, v95
	v_rcp_f32_e32 v86, v86
	v_add_f32_e32 v87, 1.0, v98
	v_mul_f32_e32 v95, 0xbfb8aa3b, v90
	v_rcp_f32_e32 v87, v87
	v_exp_f32_e32 v95, v95
	v_mul_f32_e32 v86, v96, v86
	v_mul_f32_e32 v88, v86, v88
	v_mul_f32_e32 v86, v97, v87
	v_add_f32_e32 v87, 1.0, v95
	v_rcp_f32_e32 v87, v87
	v_mul_f32_e32 v95, 0xbfb8aa3b, v91
	v_mul_f32_e32 v89, v86, v89
	v_exp_f32_e32 v95, v95
	v_mul_f32_e32 v86, v90, v87
	v_mul_f32_e32 v90, v86, v82
	v_mul_f32_e32 v86, 0xbfb8aa3b, v92
	v_exp_f32_e32 v86, v86
	v_mul_f32_e32 v87, 0xbfb8aa3b, v93
	v_exp_f32_e32 v87, v87
	v_add_f32_e32 v82, 1.0, v95
	v_rcp_f32_e32 v82, v82
	v_add_f32_e32 v86, 1.0, v86
	v_rcp_f32_e32 v86, v86
	v_add_f32_e32 v87, 1.0, v87
	v_rcp_f32_e32 v87, v87
	v_mul_f32_e32 v82, v91, v82
	v_mul_f32_e32 v91, v82, v83
	v_mul_f32_e32 v82, v92, v86
	v_mul_f32_e32 v92, v82, v84
	v_mul_f32_e32 v82, v93, v87
	v_mul_f32_e32 v85, v82, v85
	v_or_b32_e32 v82, 32, v153
	v_mad_i64_i32 v[82:83], s[12:13], v82, s59, v[114:115]
	v_lshl_add_u64 v[86:87], v[82:83], 0, v[116:117]
	v_cvt_pk_bf16_f32 v82, v94, v99
	v_cvt_pk_bf16_f32 v83, v88, v89
	v_mul_f32_e32 v88, 0xbfb8aa3b, v78
	v_exp_f32_e32 v88, v88
	v_mul_f32_e32 v89, 0xbfb8aa3b, v79
	v_exp_f32_e32 v89, v89
	v_cvt_pk_bf16_f32 v84, v90, v91
	v_add_f32_e32 v88, 1.0, v88
	v_rcp_f32_e32 v88, v88
	v_add_f32_e32 v89, 1.0, v89
	v_rcp_f32_e32 v89, v89
	v_cvt_pk_bf16_f32 v85, v92, v85
	v_mul_f32_e32 v78, v78, v88
	v_mul_f32_e32 v78, v78, v70
	v_mul_f32_e32 v70, v79, v89
	v_mul_f32_e32 v79, 0xbfb8aa3b, v80
	global_store_dwordx4 v[86:87], v[82:85], off nt
	v_exp_f32_e32 v79, v79
	s_mov_b64 s[2:3], -1
	v_mul_f32_e32 v82, 0xbfb8aa3b, v81
	v_exp_f32_e32 v82, v82
	v_mul_f32_e32 v83, v70, v71
	v_add_f32_e32 v70, 1.0, v79
	v_rcp_f32_e32 v70, v70
	v_add_f32_e32 v71, 1.0, v82
	v_mul_f32_e32 v79, 0xbfb8aa3b, v74
	v_rcp_f32_e32 v71, v71
	v_exp_f32_e32 v79, v79
	v_mul_f32_e32 v70, v80, v70
	v_mul_f32_e32 v72, v70, v72
	v_mul_f32_e32 v70, v81, v71
	v_add_f32_e32 v71, 1.0, v79
	v_rcp_f32_e32 v71, v71
	v_mul_f32_e32 v79, 0xbfb8aa3b, v75
	v_mul_f32_e32 v73, v70, v73
	v_exp_f32_e32 v79, v79
	v_mul_f32_e32 v70, v74, v71
	v_mul_f32_e32 v74, v70, v66
	v_mul_f32_e32 v70, 0xbfb8aa3b, v76
	v_exp_f32_e32 v70, v70
	v_mul_f32_e32 v71, 0xbfb8aa3b, v77
	v_exp_f32_e32 v71, v71
	v_add_f32_e32 v66, 1.0, v79
	v_rcp_f32_e32 v66, v66
	v_add_f32_e32 v70, 1.0, v70
	v_rcp_f32_e32 v70, v70
	v_add_f32_e32 v71, 1.0, v71
	v_rcp_f32_e32 v71, v71
	v_mul_f32_e32 v66, v75, v66
	v_mul_f32_e32 v75, v66, v67
	v_mul_f32_e32 v66, v76, v70
	v_mul_f32_e32 v76, v66, v68
	v_mul_f32_e32 v66, v77, v71
	v_mul_f32_e32 v69, v66, v69
	v_or_b32_e32 v66, 48, v153
	v_mad_i64_i32 v[66:67], s[12:13], v66, s59, v[114:115]
	v_lshl_add_u64 v[70:71], v[66:67], 0, v[116:117]
	v_cvt_pk_bf16_f32 v66, v78, v83
	v_cvt_pk_bf16_f32 v67, v72, v73
	v_mul_f32_e32 v72, 0xbfb8aa3b, v62
	v_exp_f32_e32 v72, v72
	v_mul_f32_e32 v73, 0xbfb8aa3b, v63
	v_exp_f32_e32 v73, v73
	v_cvt_pk_bf16_f32 v68, v74, v75
	v_cvt_pk_bf16_f32 v69, v76, v69
	global_store_dwordx4 v[70:71], v[66:69], off nt
	s_nop 1
	v_add_f32_e32 v66, 1.0, v72
	v_rcp_f32_e32 v66, v66
	v_add_f32_e32 v67, 1.0, v73
	v_rcp_f32_e32 v67, v67
	v_add_u32_e32 v68, 0x80, v153
	v_mul_f32_e32 v62, v62, v66
	v_mul_f32_e32 v62, v62, v54
	v_mul_f32_e32 v54, v63, v67
	v_mul_f32_e32 v63, 0xbfb8aa3b, v64
	v_exp_f32_e32 v63, v63
	v_mul_f32_e32 v66, 0xbfb8aa3b, v65
	v_exp_f32_e32 v66, v66
	v_mul_f32_e32 v67, v54, v55
	v_add_f32_e32 v54, 1.0, v63
	v_rcp_f32_e32 v54, v54
	v_add_f32_e32 v55, 1.0, v66
	v_mul_f32_e32 v63, 0xbfb8aa3b, v58
	v_rcp_f32_e32 v55, v55
	v_exp_f32_e32 v63, v63
	v_mul_f32_e32 v54, v64, v54
	v_mul_f32_e32 v56, v54, v56
	v_mul_f32_e32 v54, v65, v55
	v_add_f32_e32 v55, 1.0, v63
	v_rcp_f32_e32 v55, v55
	v_mul_f32_e32 v63, 0xbfb8aa3b, v59
	v_mul_f32_e32 v57, v54, v57
	v_exp_f32_e32 v63, v63
	v_mul_f32_e32 v54, v58, v55
	v_mul_f32_e32 v58, v54, v50
	v_mul_f32_e32 v54, 0xbfb8aa3b, v60
	v_exp_f32_e32 v54, v54
	v_mul_f32_e32 v55, 0xbfb8aa3b, v61
	v_exp_f32_e32 v55, v55
	v_add_f32_e32 v50, 1.0, v63
	v_rcp_f32_e32 v50, v50
	v_add_f32_e32 v54, 1.0, v54
	v_rcp_f32_e32 v54, v54
	v_add_f32_e32 v55, 1.0, v55
	v_rcp_f32_e32 v55, v55
	v_mul_f32_e32 v50, v59, v50
	v_mul_f32_e32 v59, v50, v51
	v_mul_f32_e32 v50, v60, v54
	v_mul_f32_e32 v60, v50, v52
	v_mul_f32_e32 v50, v61, v55
	v_mul_f32_e32 v53, v50, v53
	v_mad_i64_i32 v[50:51], s[12:13], v68, s59, v[114:115]
	v_lshl_add_u64 v[54:55], v[50:51], 0, v[116:117]
	v_cvt_pk_bf16_f32 v50, v62, v67
	v_cvt_pk_bf16_f32 v51, v56, v57
	v_mul_f32_e32 v56, 0xbfb8aa3b, v46
	v_exp_f32_e32 v56, v56
	v_mul_f32_e32 v57, 0xbfb8aa3b, v47
	v_exp_f32_e32 v57, v57
	v_cvt_pk_bf16_f32 v52, v58, v59
	v_add_f32_e32 v56, 1.0, v56
	v_rcp_f32_e32 v56, v56
	v_add_f32_e32 v57, 1.0, v57
	v_rcp_f32_e32 v57, v57
	v_cvt_pk_bf16_f32 v53, v60, v53
	v_mul_f32_e32 v46, v46, v56
	v_mul_f32_e32 v46, v46, v38
	v_mul_f32_e32 v38, v47, v57
	v_mul_f32_e32 v47, 0xbfb8aa3b, v48
	global_store_dwordx4 v[54:55], v[50:53], off nt
	v_exp_f32_e32 v47, v47
	s_nop 0
	v_mul_f32_e32 v50, 0xbfb8aa3b, v49
	v_exp_f32_e32 v50, v50
	v_mul_f32_e32 v51, v38, v39
	v_add_f32_e32 v38, 1.0, v47
	v_rcp_f32_e32 v38, v38
	v_add_f32_e32 v39, 1.0, v50
	v_mul_f32_e32 v47, 0xbfb8aa3b, v42
	v_rcp_f32_e32 v39, v39
	v_exp_f32_e32 v47, v47
	v_mul_f32_e32 v38, v48, v38
	v_mul_f32_e32 v40, v38, v40
	v_mul_f32_e32 v38, v49, v39
	v_add_f32_e32 v39, 1.0, v47
	v_rcp_f32_e32 v39, v39
	v_mul_f32_e32 v47, 0xbfb8aa3b, v43
	v_mul_f32_e32 v41, v38, v41
	v_exp_f32_e32 v47, v47
	v_mul_f32_e32 v38, v42, v39
	v_mul_f32_e32 v42, v38, v34
	v_mul_f32_e32 v38, 0xbfb8aa3b, v44
	v_exp_f32_e32 v38, v38
	v_mul_f32_e32 v39, 0xbfb8aa3b, v45
	v_exp_f32_e32 v39, v39
	v_add_f32_e32 v34, 1.0, v47
	v_rcp_f32_e32 v34, v34
	v_add_f32_e32 v38, 1.0, v38
	v_rcp_f32_e32 v38, v38
	v_add_f32_e32 v39, 1.0, v39
	v_rcp_f32_e32 v39, v39
	v_mul_f32_e32 v34, v43, v34
	v_mul_f32_e32 v43, v34, v35
	v_mul_f32_e32 v34, v44, v38
	v_mul_f32_e32 v44, v34, v36
	v_mul_f32_e32 v34, v45, v39
	v_mul_f32_e32 v37, v34, v37
	v_add_u32_e32 v34, 0x90, v153
	v_mad_i64_i32 v[34:35], s[12:13], v34, s59, v[114:115]
	v_lshl_add_u64 v[38:39], v[34:35], 0, v[116:117]
	v_cvt_pk_bf16_f32 v34, v46, v51
	v_cvt_pk_bf16_f32 v35, v40, v41
	v_mul_f32_e32 v40, 0xbfb8aa3b, v30
	v_exp_f32_e32 v40, v40
	v_mul_f32_e32 v41, 0xbfb8aa3b, v31
	v_exp_f32_e32 v41, v41
	v_cvt_pk_bf16_f32 v36, v42, v43
	v_add_f32_e32 v40, 1.0, v40
	v_rcp_f32_e32 v40, v40
	v_add_f32_e32 v41, 1.0, v41
	v_rcp_f32_e32 v41, v41
	v_cvt_pk_bf16_f32 v37, v44, v37
	v_mul_f32_e32 v30, v30, v40
	v_mul_f32_e32 v30, v30, v22
	v_mul_f32_e32 v22, v31, v41
	v_mul_f32_e32 v31, 0xbfb8aa3b, v32
	global_store_dwordx4 v[38:39], v[34:37], off nt
	v_exp_f32_e32 v31, v31
	s_nop 0
	v_mul_f32_e32 v34, 0xbfb8aa3b, v33
	v_exp_f32_e32 v34, v34
	v_mul_f32_e32 v35, v22, v23
	v_add_f32_e32 v22, 1.0, v31
	v_rcp_f32_e32 v22, v22
	v_add_f32_e32 v23, 1.0, v34
	v_mul_f32_e32 v31, 0xbfb8aa3b, v26
	v_rcp_f32_e32 v23, v23
	v_exp_f32_e32 v31, v31
	v_mul_f32_e32 v22, v32, v22
	v_mul_f32_e32 v24, v22, v24
	v_mul_f32_e32 v22, v33, v23
	v_add_f32_e32 v23, 1.0, v31
	v_rcp_f32_e32 v23, v23
	v_mul_f32_e32 v31, 0xbfb8aa3b, v27
	v_mul_f32_e32 v25, v22, v25
	v_exp_f32_e32 v31, v31
	v_mul_f32_e32 v22, v26, v23
	v_mul_f32_e32 v26, v22, v18
	v_mul_f32_e32 v22, 0xbfb8aa3b, v28
	v_exp_f32_e32 v22, v22
	v_mul_f32_e32 v23, 0xbfb8aa3b, v29
	v_exp_f32_e32 v23, v23
	v_add_f32_e32 v18, 1.0, v31
	v_rcp_f32_e32 v18, v18
	v_add_f32_e32 v22, 1.0, v22
	v_rcp_f32_e32 v22, v22
	v_add_f32_e32 v23, 1.0, v23
	v_rcp_f32_e32 v23, v23
	v_mul_f32_e32 v18, v27, v18
	v_mul_f32_e32 v27, v18, v19
	v_mul_f32_e32 v18, v28, v22
	v_mul_f32_e32 v28, v18, v20
	v_mul_f32_e32 v18, v29, v23
	v_mul_f32_e32 v21, v18, v21
	v_add_u32_e32 v18, 0xa0, v153
	v_mad_i64_i32 v[18:19], s[12:13], v18, s59, v[114:115]
	v_lshl_add_u64 v[22:23], v[18:19], 0, v[116:117]
	v_cvt_pk_bf16_f32 v18, v30, v35
	v_cvt_pk_bf16_f32 v19, v24, v25
	v_mul_f32_e32 v24, 0xbfb8aa3b, v14
	v_exp_f32_e32 v24, v24
	v_mul_f32_e32 v25, 0xbfb8aa3b, v15
	v_exp_f32_e32 v25, v25
	v_cvt_pk_bf16_f32 v20, v26, v27
	v_add_f32_e32 v24, 1.0, v24
	v_rcp_f32_e32 v24, v24
	v_add_f32_e32 v25, 1.0, v25
	v_rcp_f32_e32 v25, v25
	v_cvt_pk_bf16_f32 v21, v28, v21
	v_mul_f32_e32 v14, v14, v24
	v_mul_f32_e32 v14, v14, v6
	v_mul_f32_e32 v6, v15, v25
	v_mul_f32_e32 v15, 0xbfb8aa3b, v16
	global_store_dwordx4 v[22:23], v[18:21], off nt
	v_exp_f32_e32 v15, v15
	s_nop 0
	v_mul_f32_e32 v18, 0xbfb8aa3b, v17
	v_exp_f32_e32 v18, v18
	v_mul_f32_e32 v19, v6, v7
	v_add_f32_e32 v6, 1.0, v15
	v_rcp_f32_e32 v6, v6
	v_add_f32_e32 v7, 1.0, v18
	v_mul_f32_e32 v15, 0xbfb8aa3b, v10
	v_rcp_f32_e32 v7, v7
	v_exp_f32_e32 v15, v15
	v_mul_f32_e32 v6, v16, v6
	v_mul_f32_e32 v8, v6, v8
	v_mul_f32_e32 v6, v17, v7
	v_add_f32_e32 v7, 1.0, v15
	v_rcp_f32_e32 v7, v7
	v_mul_f32_e32 v15, 0xbfb8aa3b, v11
	v_mul_f32_e32 v9, v6, v9
	v_exp_f32_e32 v15, v15
	v_mul_f32_e32 v6, v10, v7
	v_mul_f32_e32 v10, v6, v2
	v_mul_f32_e32 v6, 0xbfb8aa3b, v12
	v_exp_f32_e32 v6, v6
	v_mul_f32_e32 v7, 0xbfb8aa3b, v13
	v_exp_f32_e32 v7, v7
	v_add_f32_e32 v2, 1.0, v15
	v_rcp_f32_e32 v2, v2
	v_add_f32_e32 v6, 1.0, v6
	v_rcp_f32_e32 v6, v6
	v_add_f32_e32 v7, 1.0, v7
	v_rcp_f32_e32 v7, v7
	v_mul_f32_e32 v2, v11, v2
	v_mul_f32_e32 v11, v2, v3
	v_mul_f32_e32 v2, v12, v6
	v_mul_f32_e32 v12, v2, v4
	v_mul_f32_e32 v2, v13, v7
	v_mul_f32_e32 v5, v2, v5
	v_add_u32_e32 v2, 0xb0, v153
	v_mad_i64_i32 v[2:3], s[12:13], v2, s59, v[114:115]
	v_lshl_add_u64 v[6:7], v[2:3], 0, v[116:117]
	v_cvt_pk_bf16_f32 v2, v14, v19
	v_cvt_pk_bf16_f32 v3, v8, v9
	v_cvt_pk_bf16_f32 v4, v10, v11
	v_cvt_pk_bf16_f32 v5, v12, v5
	global_store_dwordx4 v[6:7], v[2:5], off nt
	s_cbranch_vccnz .LBB0_1039
	s_andn2_b64 vcc, exec, s[4:5]
	s_cbranch_vccnz .LBB0_1038
	s_barrier
	s_branch .LBB0_1038

.LBB0_1141:
	s_cmp_gt_i32 s12, 32
	v_lshl_or_b32 v142, s13, 8, v165
	s_cselect_b32 s13, 0xc000, 0
	s_add_u32 s22, s30, s13
	v_ashrrev_i32_e32 v143, 31, v142
	s_addc_u32 s23, s31, 0
	v_lshlrev_b64 v[142:143], 2, v[142:143]
	v_lshl_add_u64 v[144:145], s[22:23], 0, v[142:143]
	v_lshl_add_u64 v[156:157], v[144:145], 0, s[16:17]
	v_add_co_u32_e32 v144, vcc, s54, v144
	v_lshl_add_u32 v171, s12, 8, v1
	s_nop 0
	v_addc_co_u32_e32 v145, vcc, 0, v145, vcc
	v_cmp_lt_i32_e32 vcc, s56, v171
	v_or_b32_e32 v177, 16, v171
	v_lshl_add_u64 v[158:159], s[18:19], 0, v[142:143]
	global_load_dwordx4 v[172:175], v[144:145], off nt
	global_load_dwordx4 v[178:181], v[158:159], off nt
	global_load_dwordx4 v[148:151], v[158:159], off offset:64 nt
	global_load_dwordx4 v[152:155], v[156:157], off offset:64 nt
	global_load_dwordx4 v[160:163], v[156:157], off offset:512 nt
	global_load_dwordx4 v[182:185], v[156:157], off offset:576 nt
	global_load_dwordx4 v[186:189], v[158:159], off offset:512 nt
	global_load_dwordx4 v[190:193], v[158:159], off offset:576 nt
	v_cndmask_b32_e32 v156, v169, v170, vcc
	v_cmp_lt_i32_e32 vcc, s56, v177
	v_add_u32_e32 v156, v156, v171
	v_ashrrev_i32_e32 v157, 31, v156
	v_cndmask_b32_e32 v206, v169, v170, vcc
	v_add_u32_e32 v206, v206, v177
	v_lshl_add_u64 v[144:145], s[28:29], 0, v[142:143]
	v_lshlrev_b64 v[156:157], 13, v[156:157]
	v_ashrrev_i32_e32 v207, 31, v206
	v_lshl_add_u64 v[158:159], v[144:145], 0, v[156:157]
	v_lshlrev_b64 v[226:227], 13, v[206:207]
	global_load_dwordx4 v[194:197], v[158:159], off offset:64 nt
	global_load_dwordx4 v[198:201], v[158:159], off offset:512 nt
	global_load_dwordx4 v[202:205], v[158:159], off offset:576 nt
	v_lshl_add_u64 v[222:223], v[144:145], 0, v[226:227]
	global_load_dwordx4 v[206:209], v[222:223], off offset:64 nt
	global_load_dwordx4 v[210:213], v[222:223], off offset:512 nt
	global_load_dwordx4 v[214:217], v[222:223], off offset:576 nt
	global_load_dwordx4 v[218:221], v[158:159], off nt
	s_nop 0
	global_load_dwordx4 v[222:225], v[222:223], off nt
	v_or_b32_e32 v158, 32, v171
	v_cmp_lt_i32_e32 vcc, s56, v158
	v_lshl_add_u64 v[156:157], s[28:29], 0, v[156:157]
	v_lshl_add_u64 v[230:231], v[156:157], 0, v[142:143]
	v_cndmask_b32_e32 v159, v169, v170, vcc
	v_add_u32_e32 v158, v159, v158
	v_ashrrev_i32_e32 v159, 31, v158
	v_lshl_add_u64 v[156:157], s[28:29], 0, v[226:227]
	v_lshlrev_b64 v[228:229], 13, v[158:159]
	v_lshl_add_u64 v[232:233], v[156:157], 0, v[142:143]
	v_lshl_add_u64 v[226:227], v[144:145], 0, v[228:229]
	s_waitcnt vmcnt(0)
	v_pk_add_f32 v[156:157], v[154:155], v[150:151]
	v_pk_add_f32 v[158:159], v[152:153], v[148:149]
	v_pk_add_f32 v[152:153], v[162:163], v[188:189]
	v_pk_add_f32 v[150:151], v[182:183], v[190:191]
	v_pk_add_f32 v[154:155], v[160:161], v[186:187]
	v_pk_add_f32 v[148:149], v[184:185], v[192:193]
	v_pk_add_f32 v[162:163], v[172:173], v[178:179]
	v_pk_add_f32 v[160:161], v[174:175], v[180:181]
	v_lshl_add_u64 v[180:181], s[28:29], 0, v[228:229]
	v_lshl_add_u64 v[180:181], v[180:181], 0, v[142:143]
	v_pk_fma_f32 v[128:129], v[128:129], v[156:157], v[196:197]
	v_pk_fma_f32 v[126:127], v[126:127], v[158:159], v[194:195]
	v_pk_fma_f32 v[106:107], v[106:107], v[150:151], v[202:203]
	v_pk_fma_f32 v[112:113], v[112:113], v[152:153], v[200:201]
	v_pk_fma_f32 v[110:111], v[110:111], v[154:155], v[198:199]
	v_pk_fma_f32 v[108:109], v[108:109], v[148:149], v[204:205]
	global_store_dwordx4 v[230:231], v[126:129], off offset:64 nt
	global_store_dwordx4 v[230:231], v[110:113], off offset:512 nt
	global_store_dwordx4 v[230:231], v[106:109], off offset:576 nt
	v_pk_fma_f32 v[120:121], v[120:121], v[156:157], v[208:209]
	v_pk_fma_f32 v[118:119], v[118:119], v[158:159], v[206:207]
	v_pk_fma_f32 v[106:107], v[114:115], v[162:163], v[222:223]
	v_or_b32_e32 v114, 48, v171
	v_cmp_lt_i32_e32 vcc, s56, v114
	v_pk_fma_f32 v[104:105], v[104:105], v[152:153], v[212:213]
	v_pk_fma_f32 v[102:103], v[102:103], v[154:155], v[210:211]
	v_cndmask_b32_e32 v115, v169, v170, vcc
	v_add_u32_e32 v114, v115, v114
	v_ashrrev_i32_e32 v115, 31, v114
	v_pk_fma_f32 v[100:101], v[100:101], v[148:149], v[216:217]
	v_pk_fma_f32 v[98:99], v[98:99], v[150:151], v[214:215]
	v_pk_fma_f32 v[124:125], v[124:125], v[160:161], v[220:221]
	v_pk_fma_f32 v[122:123], v[122:123], v[162:163], v[218:219]
	v_pk_fma_f32 v[108:109], v[116:117], v[160:161], v[224:225]
	global_store_dwordx4 v[232:233], v[118:121], off offset:64 nt
	global_store_dwordx4 v[232:233], v[102:105], off offset:512 nt
	global_store_dwordx4 v[232:233], v[98:101], off offset:576 nt
	global_store_dwordx4 v[230:231], v[122:125], off nt
	global_store_dwordx4 v[232:233], v[106:109], off nt
	v_lshlrev_b64 v[172:173], 13, v[114:115]
	v_lshl_add_u64 v[126:127], v[144:145], 0, v[172:173]
	global_load_dwordx4 v[98:101], v[226:227], off nt
	global_load_dwordx4 v[102:105], v[226:227], off offset:64 nt
	global_load_dwordx4 v[106:109], v[226:227], off offset:512 nt
	global_load_dwordx4 v[110:113], v[226:227], off offset:576 nt
	global_load_dwordx4 v[114:117], v[126:127], off nt
	global_load_dwordx4 v[118:121], v[126:127], off offset:64 nt
	global_load_dwordx4 v[122:125], v[126:127], off offset:512 nt
	s_nop 0
	global_load_dwordx4 v[126:129], v[126:127], off offset:576 nt
	v_cmp_lt_i32_e32 vcc, s57, v171
	v_lshl_add_u64 v[172:173], s[28:29], 0, v[172:173]
	v_lshl_add_u64 v[172:173], v[172:173], 0, v[142:143]
	v_cndmask_b32_e32 v174, v169, v170, vcc
	v_cmp_lt_i32_e32 vcc, s59, v171
	v_add3_u32 v174, v171, v174, s58
	v_ashrrev_i32_e32 v175, 31, v174
	v_cndmask_b32_e32 v177, v169, v170, vcc
	v_lshlrev_b64 v[174:175], 13, v[174:175]
	v_lshl_add_u64 v[178:179], v[144:145], 0, v[174:175]
	v_cmp_lt_i32_e32 vcc, s61, v171
	s_waitcnt vmcnt(7)
	v_pk_fma_f32 v[96:97], v[96:97], v[160:161], v[100:101]
	v_pk_fma_f32 v[94:95], v[94:95], v[162:163], v[98:99]
	s_waitcnt vmcnt(5)
	v_pk_fma_f32 v[78:79], v[78:79], v[154:155], v[106:107]
	v_pk_fma_f32 v[92:93], v[92:93], v[156:157], v[104:105]
	v_pk_fma_f32 v[90:91], v[90:91], v[158:159], v[102:103]
	v_pk_fma_f32 v[80:81], v[80:81], v[152:153], v[108:109]
	s_waitcnt vmcnt(4)
	v_pk_fma_f32 v[76:77], v[76:77], v[148:149], v[112:113]
	v_pk_fma_f32 v[74:75], v[74:75], v[150:151], v[110:111]
	s_waitcnt vmcnt(3)
	v_pk_fma_f32 v[88:89], v[88:89], v[160:161], v[116:117]
	v_pk_fma_f32 v[86:87], v[86:87], v[162:163], v[114:115]
	s_waitcnt vmcnt(2)
	v_pk_fma_f32 v[84:85], v[84:85], v[156:157], v[120:121]
	v_pk_fma_f32 v[82:83], v[82:83], v[158:159], v[118:119]
	s_waitcnt vmcnt(1)
	v_pk_fma_f32 v[72:73], v[72:73], v[152:153], v[124:125]
	v_pk_fma_f32 v[70:71], v[70:71], v[154:155], v[122:123]
	s_waitcnt vmcnt(0)
	v_pk_fma_f32 v[68:69], v[68:69], v[148:149], v[128:129]
	v_pk_fma_f32 v[66:67], v[66:67], v[150:151], v[126:127]
	global_store_dwordx4 v[180:181], v[94:97], off nt
	global_store_dwordx4 v[180:181], v[90:93], off offset:64 nt
	global_store_dwordx4 v[180:181], v[78:81], off offset:512 nt
	global_store_dwordx4 v[180:181], v[74:77], off offset:576 nt
	global_store_dwordx4 v[172:173], v[86:89], off nt
	global_store_dwordx4 v[172:173], v[82:85], off offset:64 nt
	global_store_dwordx4 v[172:173], v[70:73], off offset:512 nt
	global_store_dwordx4 v[172:173], v[66:69], off offset:576 nt
	v_add3_u32 v78, v171, v177, s60
	v_ashrrev_i32_e32 v79, 31, v78
	v_lshlrev_b64 v[98:99], 13, v[78:79]
	global_load_dwordx4 v[66:69], v[178:179], off nt
	global_load_dwordx4 v[70:73], v[178:179], off offset:64 nt
	global_load_dwordx4 v[74:77], v[178:179], off offset:512 nt
	global_load_dwordx4 v[78:81], v[178:179], off offset:576 nt
	v_lshl_add_u64 v[94:95], v[144:145], 0, v[98:99]
	global_load_dwordx4 v[82:85], v[94:95], off nt
	global_load_dwordx4 v[86:89], v[94:95], off offset:64 nt
	global_load_dwordx4 v[90:93], v[94:95], off offset:512 nt
	s_nop 0
	global_load_dwordx4 v[94:97], v[94:95], off offset:576 nt
	v_cndmask_b32_e32 v100, v169, v170, vcc
	v_cmp_lt_i32_e32 vcc, s63, v171
	v_lshl_add_u64 v[102:103], s[28:29], 0, v[174:175]
	v_add3_u32 v100, v171, v100, s62
	v_cndmask_b32_e32 v106, v169, v170, vcc
	v_lshl_add_u64 v[98:99], s[28:29], 0, v[98:99]
	v_lshl_add_u64 v[102:103], v[102:103], 0, v[142:143]
	v_ashrrev_i32_e32 v101, 31, v100
	v_lshl_add_u64 v[98:99], v[98:99], 0, v[142:143]
	v_lshlrev_b64 v[100:101], 13, v[100:101]
	v_lshl_add_u64 v[104:105], v[144:145], 0, v[100:101]
	s_and_b64 vcc, exec, s[2:3]
	s_mov_b64 s[2:3], -1
	s_waitcnt vmcnt(7)
	v_pk_fma_f32 v[64:65], v[64:65], v[160:161], v[68:69]
	v_pk_fma_f32 v[62:63], v[62:63], v[162:163], v[66:67]
	s_waitcnt vmcnt(5)
	v_pk_fma_f32 v[46:47], v[46:47], v[154:155], v[74:75]
	v_pk_fma_f32 v[60:61], v[60:61], v[156:157], v[72:73]
	v_pk_fma_f32 v[58:59], v[58:59], v[158:159], v[70:71]
	v_pk_fma_f32 v[48:49], v[48:49], v[152:153], v[76:77]
	s_waitcnt vmcnt(4)
	v_pk_fma_f32 v[44:45], v[44:45], v[148:149], v[80:81]
	v_pk_fma_f32 v[42:43], v[42:43], v[150:151], v[78:79]
	s_waitcnt vmcnt(3)
	v_pk_fma_f32 v[56:57], v[56:57], v[160:161], v[84:85]
	v_pk_fma_f32 v[54:55], v[54:55], v[162:163], v[82:83]
	s_waitcnt vmcnt(2)
	v_pk_fma_f32 v[52:53], v[52:53], v[156:157], v[88:89]
	v_pk_fma_f32 v[50:51], v[50:51], v[158:159], v[86:87]
	s_waitcnt vmcnt(1)
	v_pk_fma_f32 v[40:41], v[40:41], v[152:153], v[92:93]
	v_pk_fma_f32 v[38:39], v[38:39], v[154:155], v[90:91]
	s_waitcnt vmcnt(0)
	v_pk_fma_f32 v[36:37], v[36:37], v[148:149], v[96:97]
	v_pk_fma_f32 v[34:35], v[34:35], v[150:151], v[94:95]
	global_store_dwordx4 v[102:103], v[62:65], off nt
	global_store_dwordx4 v[102:103], v[58:61], off offset:64 nt
	global_store_dwordx4 v[102:103], v[46:49], off offset:512 nt
	global_store_dwordx4 v[102:103], v[42:45], off offset:576 nt
	global_store_dwordx4 v[98:99], v[54:57], off nt
	global_store_dwordx4 v[98:99], v[50:53], off offset:64 nt
	global_store_dwordx4 v[98:99], v[38:41], off offset:512 nt
	global_store_dwordx4 v[98:99], v[34:37], off offset:576 nt
	v_add3_u32 v46, v171, v106, s64
	v_ashrrev_i32_e32 v47, 31, v46
	v_lshlrev_b64 v[66:67], 13, v[46:47]
	global_load_dwordx4 v[34:37], v[104:105], off nt
	global_load_dwordx4 v[38:41], v[104:105], off offset:64 nt
	v_lshl_add_u64 v[62:63], v[144:145], 0, v[66:67]
	global_load_dwordx4 v[42:45], v[104:105], off offset:512 nt
	global_load_dwordx4 v[46:49], v[104:105], off offset:576 nt
	global_load_dwordx4 v[50:53], v[62:63], off nt
	global_load_dwordx4 v[54:57], v[62:63], off offset:64 nt
	global_load_dwordx4 v[58:61], v[62:63], off offset:512 nt
	s_nop 0
	global_load_dwordx4 v[62:65], v[62:63], off offset:576 nt
	v_lshl_add_u64 v[68:69], s[28:29], 0, v[100:101]
	v_lshl_add_u64 v[66:67], s[28:29], 0, v[66:67]
	v_lshl_add_u64 v[68:69], v[68:69], 0, v[142:143]
	v_lshl_add_u64 v[66:67], v[66:67], 0, v[142:143]
	s_waitcnt vmcnt(7)
	v_pk_fma_f32 v[32:33], v[32:33], v[160:161], v[36:37]
	v_pk_fma_f32 v[30:31], v[30:31], v[162:163], v[34:35]
	s_waitcnt vmcnt(6)
	v_pk_fma_f32 v[28:29], v[28:29], v[156:157], v[40:41]
	v_pk_fma_f32 v[26:27], v[26:27], v[158:159], v[38:39]
	s_waitcnt vmcnt(5)
	v_pk_fma_f32 v[16:17], v[16:17], v[152:153], v[44:45]
	v_pk_fma_f32 v[14:15], v[14:15], v[154:155], v[42:43]
	s_waitcnt vmcnt(4)
	v_pk_fma_f32 v[12:13], v[12:13], v[148:149], v[48:49]
	v_pk_fma_f32 v[10:11], v[10:11], v[150:151], v[46:47]
	s_waitcnt vmcnt(3)
	v_pk_fma_f32 v[24:25], v[24:25], v[160:161], v[52:53]
	v_pk_fma_f32 v[22:23], v[22:23], v[162:163], v[50:51]
	s_waitcnt vmcnt(2)
	v_pk_fma_f32 v[20:21], v[20:21], v[156:157], v[56:57]
	v_pk_fma_f32 v[18:19], v[18:19], v[158:159], v[54:55]
	s_waitcnt vmcnt(1)
	v_pk_fma_f32 v[8:9], v[8:9], v[152:153], v[60:61]
	v_pk_fma_f32 v[6:7], v[6:7], v[154:155], v[58:59]
	s_waitcnt vmcnt(0)
	v_pk_fma_f32 v[4:5], v[4:5], v[148:149], v[64:65]
	v_pk_fma_f32 v[2:3], v[2:3], v[150:151], v[62:63]
	global_store_dwordx4 v[68:69], v[30:33], off nt
	global_store_dwordx4 v[68:69], v[26:29], off offset:64 nt
	global_store_dwordx4 v[68:69], v[14:17], off offset:512 nt
	global_store_dwordx4 v[68:69], v[10:13], off offset:576 nt
	global_store_dwordx4 v[66:67], v[22:25], off nt
	global_store_dwordx4 v[66:67], v[18:21], off offset:64 nt
	global_store_dwordx4 v[66:67], v[6:9], off offset:512 nt
	global_store_dwordx4 v[66:67], v[2:5], off offset:576 nt
	s_cbranch_vccnz .LBB0_1126
	s_andn2_b64 vcc, exec, s[6:7]
	s_cbranch_vccnz .LBB0_1125
	s_barrier
	s_branch .LBB0_1125

.LBB0_1213:
	s_waitcnt lgkmcnt(0)
	global_load_dwordx4 v[4:7], v[22:23], off offset:-3072 nt
	global_load_dwordx4 v[8:11], v[22:23], off offset:-2048 nt
	global_load_dwordx4 v[0:3], v[22:23], off nt
	global_load_dwordx4 v[32:35], v[22:23], off offset:-1024 nt
	v_add_co_u32_e32 v56, vcc, 0xfffff000, v22
	s_add_i32 s34, s34, s68
	s_nop 0
	v_addc_co_u32_e32 v57, vcc, -1, v23, vcc
	global_load_dwordx4 v[36:39], v[56:57], off offset:-3072 nt
	global_load_dwordx4 v[40:43], v[56:57], off offset:-2048 nt
	global_load_dwordx4 v[44:47], v[56:57], off offset:-1024 nt
	global_load_dwordx4 v[48:51], v[22:23], off offset:-4096 nt
	global_load_dwordx4 v[52:55], v[12:13], off nt
	s_cmpk_lt_i32 s34, 0x4000
	s_waitcnt vmcnt(0)
	v_mul_f32_e32 v81, v4, v4
	v_pk_mul_f32 v[58:59], v[10:11], v[10:11]
	v_pk_mul_f32 v[60:61], v[8:9], v[8:9]
	v_mul_f32_e32 v62, v33, v33
	v_mul_f32_e32 v64, v35, v35
	v_mul_f32_e32 v79, v2, v2
	v_mul_f32_e32 v87, v3, v3
	v_pk_mov_b32 v[66:67], v[60:61], v[58:59] op_sel:[1,0]
	v_mov_b32_e32 v61, v59
	v_pk_fma_f32 v[58:59], v[32:33], v[32:33], v[62:63] op_sel_hi:[1,1,0]
	v_pk_fma_f32 v[62:63], v[34:35], v[34:35], v[64:65] op_sel_hi:[1,1,0]
	v_mov_b32_e32 v68, v37
	v_mov_b32_e32 v69, v41
	v_mov_b32_e32 v72, v39
	v_mov_b32_e32 v73, v43
	v_mov_b32_e32 v64, v36
	v_mov_b32_e32 v65, v40
	v_mov_b32_e32 v70, v38
	v_mov_b32_e32 v71, v42
	v_pk_mul_f32 v[74:75], v[46:47], v[46:47]
	v_pk_mul_f32 v[76:77], v[44:45], v[44:45]
	v_pk_add_f32 v[60:61], v[66:67], v[60:61]
	v_mov_b32_e32 v59, v79
	v_mov_b32_e32 v63, v87
	v_pk_mul_f32 v[66:67], v[68:69], v[68:69]
	v_pk_mul_f32 v[68:69], v[72:73], v[72:73]
	v_pk_mov_b32 v[72:73], v[76:77], v[74:75] op_sel:[1,0]
	v_mov_b32_e32 v77, v75
	v_pk_add_f32 v[58:59], v[58:59], v[62:63]
	v_pk_fma_f32 v[62:63], v[64:65], v[64:65], v[66:67]
	v_pk_fma_f32 v[64:65], v[70:71], v[70:71], v[68:69]
	v_mul_f32_e32 v78, v49, v49
	v_mul_f32_e32 v80, v51, v51
	v_pk_add_f32 v[66:67], v[72:73], v[76:77]
	v_pk_add_f32 v[62:63], v[62:63], v[64:65]
	v_mul_f32_e32 v82, v5, v5
	v_mul_f32_e32 v83, v6, v6
	v_mul_f32_e32 v84, v7, v7
	v_pk_fma_f32 v[74:75], v[48:49], v[48:49], v[78:79] op_sel_hi:[1,1,0]
	v_pk_fma_f32 v[78:79], v[50:51], v[50:51], v[80:81] op_sel_hi:[1,1,0]
	v_pk_add_f32 v[64:65], v[66:67], v[66:67] op_sel:[0,1] op_sel_hi:[1,0]
	v_pk_add_f32 v[62:63], v[62:63], v[62:63] op_sel:[0,1] op_sel_hi:[1,0]
	v_mov_b32_e32 v75, v83
	v_mov_b32_e32 v79, v84
	v_mov_b32_e32 v65, v82
	v_mov_b32_e32 v63, v81
	v_pk_add_f32 v[66:67], v[74:75], v[78:79]
	v_pk_add_f32 v[62:63], v[62:63], v[64:65]
	v_mul_f32_e32 v85, v0, v0
	v_pk_add_f32 v[62:63], v[62:63], v[66:67]
	v_mul_f32_e32 v86, v1, v1
	v_pk_add_f32 v[60:61], v[60:61], v[60:61] op_sel:[0,1] op_sel_hi:[1,0]
	v_pk_add_f32 v[62:63], v[62:63], v[62:63] op_sel:[0,1] op_sel_hi:[1,0]
	v_mov_b32_e32 v61, v86
	v_mov_b32_e32 v63, v85
	v_pk_add_f32 v[60:61], v[62:63], v[60:61]
	s_nop 0
	v_pk_add_f32 v[58:59], v[60:61], v[58:59]
	s_nop 0
	v_add_f32_e32 v58, v58, v59
	ds_bpermute_b32 v59, v24, v58
	s_waitcnt lgkmcnt(0)
	v_add_f32_e32 v58, v58, v59
	ds_bpermute_b32 v59, v25, v58
	s_waitcnt lgkmcnt(0)
	v_add_f32_e32 v58, v58, v59
	ds_bpermute_b32 v59, v26, v58
	s_waitcnt lgkmcnt(0)
	v_add_f32_e32 v58, v58, v59
	ds_bpermute_b32 v59, v27, v58
	s_waitcnt lgkmcnt(0)
	v_add_f32_e32 v58, v58, v59
	ds_bpermute_b32 v59, v28, v58
	s_waitcnt lgkmcnt(0)
	v_add_f32_e32 v58, v58, v59
	ds_bpermute_b32 v59, v29, v58
	s_waitcnt lgkmcnt(0)
	v_add_f32_e32 v58, v58, v59
	v_fmamk_f32 v58, v58, 0x3a000000, v30
	v_mul_f32_e32 v59, 0x4f800000, v58
	v_cmp_gt_f32_e32 vcc, s4, v58
	s_nop 1
	v_cndmask_b32_e32 v58, v58, v59, vcc
	v_sqrt_f32_e32 v59, v58
	s_nop 0
	v_add_u32_e32 v60, -1, v59
	v_add_u32_e32 v61, 1, v59
	v_fma_f32 v62, -v60, v59, v58
	v_fma_f32 v63, -v61, v59, v58
	v_cmp_ge_f32_e64 s[0:1], 0, v62
	s_nop 1
	v_cndmask_b32_e64 v59, v59, v60, s[0:1]
	v_cmp_lt_f32_e64 s[0:1], 0, v63
	s_nop 1
	v_cndmask_b32_e64 v59, v59, v61, s[0:1]
	v_mul_f32_e32 v60, 0x37800000, v59
	v_cndmask_b32_e32 v59, v59, v60, vcc
	v_cmp_class_f32_e32 vcc, v58, v31
	s_nop 1
	v_cndmask_b32_e32 v58, v59, v58, vcc
	v_div_scale_f32 v59, s[0:1], v58, v58, 1.0
	v_rcp_f32_e32 v60, v59
	v_div_scale_f32 v61, vcc, 1.0, v58, 1.0
	v_fma_f32 v62, -v59, v60, 1.0
	v_fmac_f32_e32 v60, v62, v60
	v_mul_f32_e32 v62, v61, v60
	v_fma_f32 v63, -v59, v62, v61
	v_fmac_f32_e32 v62, v63, v60
	v_fma_f32 v59, -v59, v62, v61
	v_div_fmas_f32 v59, v59, v60, v62
	v_div_fixup_f32 v58, v59, v58, 1.0
	v_pk_mul_f32 v[36:37], v[36:37], v[58:59] op_sel_hi:[1,0]
	v_pk_mul_f32 v[38:39], v[38:39], v[58:59] op_sel_hi:[1,0]
	v_pk_mul_f32 v[36:37], v[52:53], v[36:37]
	v_pk_mul_f32 v[38:39], v[54:55], v[38:39]
	global_store_dwordx4 v[56:57], v[36:39], off offset:-3072 nt
	global_load_dwordx4 v[36:39], v[12:13], off offset:1024 nt
	v_pk_mul_f32 v[42:43], v[42:43], v[58:59] op_sel_hi:[1,0]
	v_pk_mul_f32 v[40:41], v[40:41], v[58:59] op_sel_hi:[1,0]
	v_pk_mul_f32 v[6:7], v[6:7], v[58:59] op_sel_hi:[1,0]
	v_pk_mul_f32 v[4:5], v[4:5], v[58:59] op_sel_hi:[1,0]
	v_pk_mul_f32 v[10:11], v[10:11], v[58:59] op_sel_hi:[1,0]
	v_pk_mul_f32 v[8:9], v[8:9], v[58:59] op_sel_hi:[1,0]
	v_pk_mul_f32 v[2:3], v[2:3], v[58:59] op_sel_hi:[1,0]
	v_pk_mul_f32 v[0:1], v[0:1], v[58:59] op_sel_hi:[1,0]
	s_waitcnt vmcnt(0)
	v_pk_mul_f32 v[36:37], v[36:37], v[40:41]
	v_pk_mul_f32 v[38:39], v[38:39], v[42:43]
	global_store_dwordx4 v[56:57], v[36:39], off offset:-2048 nt
	global_load_dwordx4 v[36:39], v[12:13], off offset:2048 nt
	v_pk_mul_f32 v[40:41], v[46:47], v[58:59] op_sel_hi:[1,0]
	v_pk_mul_f32 v[42:43], v[44:45], v[58:59] op_sel_hi:[1,0]
	s_waitcnt vmcnt(0)
	v_pk_mul_f32 v[38:39], v[38:39], v[40:41]
	v_pk_mul_f32 v[36:37], v[36:37], v[42:43]
	global_store_dwordx4 v[56:57], v[36:39], off offset:-1024 nt
	global_load_dwordx4 v[36:39], v[12:13], off offset:3072 nt
	v_pk_mul_f32 v[40:41], v[50:51], v[58:59] op_sel_hi:[1,0]
	v_pk_mul_f32 v[42:43], v[48:49], v[58:59] op_sel_hi:[1,0]
	s_waitcnt vmcnt(0)
	v_pk_mul_f32 v[38:39], v[38:39], v[40:41]
	v_pk_mul_f32 v[36:37], v[36:37], v[42:43]
	global_store_dwordx4 v[22:23], v[36:39], off offset:-4096 nt
	global_load_dwordx4 v[36:39], v[14:15], off nt
	s_waitcnt vmcnt(0)
	v_pk_mul_f32 v[4:5], v[36:37], v[4:5]
	v_pk_mul_f32 v[6:7], v[38:39], v[6:7]
	global_store_dwordx4 v[22:23], v[4:7], off offset:-3072 nt
	global_load_dwordx4 v[4:7], v[16:17], off nt
	s_waitcnt vmcnt(0)
	v_pk_mul_f32 v[4:5], v[8:9], v[4:5]
	v_pk_mul_f32 v[6:7], v[10:11], v[6:7]
	global_store_dwordx4 v[22:23], v[4:7], off offset:-2048 nt
	global_load_dwordx4 v[4:7], v[18:19], off nt
	v_pk_mul_f32 v[8:9], v[34:35], v[58:59] op_sel_hi:[1,0]
	v_pk_mul_f32 v[10:11], v[32:33], v[58:59] op_sel_hi:[1,0]
	s_waitcnt vmcnt(0)
	v_pk_mul_f32 v[6:7], v[8:9], v[6:7]
	v_pk_mul_f32 v[4:5], v[10:11], v[4:5]
	global_store_dwordx4 v[22:23], v[4:7], off offset:-1024 nt
	global_load_dwordx4 v[4:7], v[20:21], off nt
	s_waitcnt vmcnt(0)
	v_pk_mul_f32 v[0:1], v[0:1], v[4:5]
	v_pk_mul_f32 v[2:3], v[2:3], v[6:7]
	global_store_dwordx4 v[22:23], v[0:3], off nt
	v_lshl_add_u64 v[22:23], v[22:23], 0, s[2:3]
	s_cbranch_scc1 .LBB0_1213
